# GEMM K-loops: removed the mid-segment s_setprio 0/1 flip between the two 16-MFMA blocks of every super-phase
# speedup vs baseline: 1.0084x; 1.0084x over previous
.LBB0_105:
	ds_read_b128 v[142:145], v160
	ds_read_b128 v[146:149], v160 offset:1024
	ds_read_b128 v[150:153], v160 offset:2048
	ds_read_b128 v[154:157], v160 offset:3072
	ds_read_b128 v[164:167], v161
	ds_read_b128 v[168:171], v161 offset:1024
	ds_read_b128 v[172:175], v161 offset:2048
	ds_read_b128 v[176:179], v161 offset:3072
	s_add_u32 s54, s52, 0xfffc0080
	s_addc_u32 s55, s53, -1
	s_cmp_eq_u32 s62, 12
	s_cselect_b32 s57, s1, s55
	s_cselect_b32 s56, s3, s54
	s_cselect_b32 s55, s45, s59
	s_cselect_b32 s54, s51, s58
	v_lshl_add_u64 v[214:215], s[52:53], 0, v[138:139]
	s_add_i32 m0, s25, 0xc000
	ds_read_b128 v[180:183], v162
	ds_read_b128 v[186:189], v162 offset:1024
	ds_read_b128 v[190:193], v162 offset:2048
	ds_read_b128 v[194:197], v162 offset:3072
	ds_read_b128 v[198:201], v162 offset:4096
	ds_read_b128 v[202:205], v162 offset:5120
	ds_read_b128 v[206:209], v162 offset:6144
	ds_read_b128 v[210:213], v162 offset:7168
	global_load_lds_dwordx4 v[214:215], off
	v_lshl_add_u64 v[214:215], s[52:53], 0, v[140:141]
	s_add_i32 m0, s25, 0xe000
	s_nop 0
	global_load_lds_dwordx4 v[214:215], off
	s_waitcnt vmcnt(8)
	s_waitcnt lgkmcnt(0)
	s_barrier
	s_setprio 1
	s_waitcnt lgkmcnt(0)
	v_mfma_f32_16x16x32_bf16 v[124:127], v[142:145], v[180:183], v[124:127]
	v_mfma_f32_16x16x32_bf16 v[120:123], v[150:153], v[180:183], v[120:123]
	v_mfma_f32_16x16x32_bf16 v[116:119], v[142:145], v[190:193], v[116:119]
	v_mfma_f32_16x16x32_bf16 v[108:111], v[150:153], v[190:193], v[108:111]
	v_mfma_f32_16x16x32_bf16 v[100:103], v[142:145], v[198:201], v[100:103]
	v_mfma_f32_16x16x32_bf16 v[92:95], v[150:153], v[198:201], v[92:95]
	v_mfma_f32_16x16x32_bf16 v[84:87], v[142:145], v[206:209], v[84:87]
	v_mfma_f32_16x16x32_bf16 v[76:79], v[150:153], v[206:209], v[76:79]
	v_mfma_f32_16x16x32_bf16 v[124:127], v[146:149], v[186:189], v[124:127]
	v_mfma_f32_16x16x32_bf16 v[120:123], v[154:157], v[186:189], v[120:123]
	v_mfma_f32_16x16x32_bf16 v[116:119], v[146:149], v[194:197], v[116:119]
	v_mfma_f32_16x16x32_bf16 v[108:111], v[154:157], v[194:197], v[108:111]
	v_mfma_f32_16x16x32_bf16 v[100:103], v[146:149], v[202:205], v[100:103]
	v_mfma_f32_16x16x32_bf16 v[92:95], v[154:157], v[202:205], v[92:95]
	v_mfma_f32_16x16x32_bf16 v[84:87], v[146:149], v[210:213], v[84:87]
	v_mfma_f32_16x16x32_bf16 v[76:79], v[154:157], v[210:213], v[76:79]
	v_mfma_f32_16x16x32_bf16 v[112:115], v[164:167], v[180:183], v[112:115]
	v_mfma_f32_16x16x32_bf16 v[104:107], v[172:175], v[180:183], v[104:107]
	v_mfma_f32_16x16x32_bf16 v[96:99], v[164:167], v[190:193], v[96:99]
	v_mfma_f32_16x16x32_bf16 v[88:91], v[172:175], v[190:193], v[88:91]
	v_mfma_f32_16x16x32_bf16 v[80:83], v[164:167], v[198:201], v[80:83]
	v_mfma_f32_16x16x32_bf16 v[72:75], v[172:175], v[198:201], v[72:75]
	v_mfma_f32_16x16x32_bf16 v[68:71], v[164:167], v[206:209], v[68:71]
	v_mfma_f32_16x16x32_bf16 v[64:67], v[172:175], v[206:209], v[64:67]
	v_mfma_f32_16x16x32_bf16 v[112:115], v[168:171], v[186:189], v[112:115]
	v_mfma_f32_16x16x32_bf16 v[104:107], v[176:179], v[186:189], v[104:107]
	v_mfma_f32_16x16x32_bf16 v[96:99], v[168:171], v[194:197], v[96:99]
	v_mfma_f32_16x16x32_bf16 v[88:91], v[176:179], v[194:197], v[88:91]
	v_mfma_f32_16x16x32_bf16 v[80:83], v[168:171], v[202:205], v[80:83]
	v_mfma_f32_16x16x32_bf16 v[72:75], v[176:179], v[202:205], v[72:75]
	v_mfma_f32_16x16x32_bf16 v[68:71], v[168:171], v[210:213], v[68:71]
	v_mfma_f32_16x16x32_bf16 v[64:67], v[176:179], v[210:213], v[64:67]
	s_setprio 0
	s_barrier
	s_add_i32 s63, s60, s24
	v_lshl_add_u64 v[214:215], s[54:55], 0, v[130:131]
	s_mov_b32 m0, s63
	ds_read_b128 v[180:183], v162 offset:16384
	ds_read_b128 v[186:189], v162 offset:17408
	ds_read_b128 v[190:193], v162 offset:18432
	ds_read_b128 v[194:197], v162 offset:19456
	ds_read_b128 v[198:201], v162 offset:20480
	ds_read_b128 v[202:205], v162 offset:21504
	ds_read_b128 v[206:209], v162 offset:22528
	ds_read_b128 v[210:213], v162 offset:23552
	global_load_lds_dwordx4 v[214:215], off
	s_add_i32 m0, s63, 0x2000
	s_add_u32 s64, s54, 0x40000
	v_lshl_add_u64 v[216:217], s[54:55], 0, v[134:135]
	s_addc_u32 s65, s55, 0
	s_add_i32 s63, s61, s24
	global_load_lds_dwordx4 v[216:217], off
	v_lshl_add_u64 v[218:219], s[64:65], 0, v[130:131]
	s_mov_b32 m0, s63
	v_lshl_add_u64 v[220:221], s[56:57], 0, v[132:133]
	global_load_lds_dwordx4 v[218:219], off
	v_lshl_add_u64 v[218:219], s[64:65], 0, v[134:135]
	s_add_i32 m0, s63, 0x2000
	s_nop 0
	global_load_lds_dwordx4 v[218:219], off
	v_lshl_add_u64 v[218:219], s[56:57], 0, v[128:129]
	s_mov_b32 m0, s25
	s_nop 0
	global_load_lds_dwordx4 v[218:219], off
	s_mov_b32 m0, s26
	s_nop 0
	global_load_lds_dwordx4 v[220:221], off
	s_waitcnt vmcnt(8)
	s_waitcnt lgkmcnt(0)
	s_barrier
	s_setprio 1
	s_waitcnt lgkmcnt(0)
	v_mfma_f32_16x16x32_bf16 v[60:63], v[142:145], v[180:183], v[60:63]
	v_mfma_f32_16x16x32_bf16 v[56:59], v[150:153], v[180:183], v[56:59]
	v_mfma_f32_16x16x32_bf16 v[52:55], v[142:145], v[190:193], v[52:55]
	v_mfma_f32_16x16x32_bf16 v[48:51], v[150:153], v[190:193], v[48:51]
	v_mfma_f32_16x16x32_bf16 v[36:39], v[142:145], v[198:201], v[36:39]
	v_mfma_f32_16x16x32_bf16 v[32:35], v[150:153], v[198:201], v[32:35]
	v_mfma_f32_16x16x32_bf16 v[20:23], v[142:145], v[206:209], v[20:23]
	v_mfma_f32_16x16x32_bf16 v[16:19], v[150:153], v[206:209], v[16:19]
	v_mfma_f32_16x16x32_bf16 v[60:63], v[146:149], v[186:189], v[60:63]
	v_mfma_f32_16x16x32_bf16 v[56:59], v[154:157], v[186:189], v[56:59]
	v_mfma_f32_16x16x32_bf16 v[52:55], v[146:149], v[194:197], v[52:55]
	v_mfma_f32_16x16x32_bf16 v[48:51], v[154:157], v[194:197], v[48:51]
	v_mfma_f32_16x16x32_bf16 v[36:39], v[146:149], v[202:205], v[36:39]
	v_mfma_f32_16x16x32_bf16 v[32:35], v[154:157], v[202:205], v[32:35]
	v_mfma_f32_16x16x32_bf16 v[20:23], v[146:149], v[210:213], v[20:23]
	v_mfma_f32_16x16x32_bf16 v[16:19], v[154:157], v[210:213], v[16:19]
	v_mfma_f32_16x16x32_bf16 v[44:47], v[164:167], v[180:183], v[44:47]
	v_mfma_f32_16x16x32_bf16 v[40:43], v[172:175], v[180:183], v[40:43]
	v_mfma_f32_16x16x32_bf16 v[28:31], v[164:167], v[190:193], v[28:31]
	v_mfma_f32_16x16x32_bf16 v[24:27], v[172:175], v[190:193], v[24:27]
	v_mfma_f32_16x16x32_bf16 v[12:15], v[164:167], v[198:201], v[12:15]
	v_mfma_f32_16x16x32_bf16 v[8:11], v[172:175], v[198:201], v[8:11]
	v_mfma_f32_16x16x32_bf16 v[4:7], v[164:167], v[206:209], v[4:7]
	v_mfma_f32_16x16x32_bf16 v[0:3], v[172:175], v[206:209], v[0:3]
	v_mfma_f32_16x16x32_bf16 v[44:47], v[168:171], v[186:189], v[44:47]
	v_mfma_f32_16x16x32_bf16 v[40:43], v[176:179], v[186:189], v[40:43]
	v_mfma_f32_16x16x32_bf16 v[28:31], v[168:171], v[194:197], v[28:31]
	v_mfma_f32_16x16x32_bf16 v[24:27], v[176:179], v[194:197], v[24:27]
	v_mfma_f32_16x16x32_bf16 v[12:15], v[168:171], v[202:205], v[12:15]
	v_mfma_f32_16x16x32_bf16 v[8:11], v[176:179], v[202:205], v[8:11]
	v_mfma_f32_16x16x32_bf16 v[4:7], v[168:171], v[210:213], v[4:7]
	v_mfma_f32_16x16x32_bf16 v[0:3], v[176:179], v[210:213], v[0:3]
	s_setprio 0
	s_barrier
	s_add_i32 s63, 0, 0x18000
	v_add_u32_e32 v136, s63, v159
	s_add_i32 s64, 0, 0x1c000
	ds_read_b128 v[142:145], v136
	ds_read_b128 v[146:149], v136 offset:1024
	ds_read_b128 v[150:153], v136 offset:2048
	ds_read_b128 v[154:157], v136 offset:3072
	v_add_u32_e32 v136, s64, v159
	ds_read_b128 v[164:167], v136
	ds_read_b128 v[168:171], v136 offset:1024
	ds_read_b128 v[172:175], v136 offset:2048
	ds_read_b128 v[176:179], v136 offset:3072
	s_add_u32 s56, s56, 0x40000
	s_addc_u32 s57, s57, 0
	s_mov_b32 m0, s27
	v_lshl_add_u64 v[222:223], s[56:57], 0, v[128:129]
	ds_read_b128 v[180:183], v162 offset:32768
	ds_read_b128 v[186:189], v162 offset:33792
	ds_read_b128 v[190:193], v162 offset:34816
	ds_read_b128 v[194:197], v162 offset:35840
	ds_read_b128 v[198:201], v162 offset:36864
	ds_read_b128 v[202:205], v162 offset:37888
	ds_read_b128 v[206:209], v162 offset:38912
	ds_read_b128 v[210:213], v162 offset:39936
	global_load_lds_dwordx4 v[222:223], off
	v_lshl_add_u64 v[222:223], s[56:57], 0, v[132:133]
	s_mov_b32 m0, s28
	s_nop 0
	global_load_lds_dwordx4 v[222:223], off
	s_waitcnt vmcnt(8)
	s_waitcnt lgkmcnt(0)
	s_barrier
	s_setprio 1
	s_waitcnt lgkmcnt(0)
	v_mfma_f32_16x16x32_bf16 v[124:127], v[142:145], v[180:183], v[124:127]
	v_mfma_f32_16x16x32_bf16 v[120:123], v[150:153], v[180:183], v[120:123]
	v_mfma_f32_16x16x32_bf16 v[116:119], v[142:145], v[190:193], v[116:119]
	v_mfma_f32_16x16x32_bf16 v[108:111], v[150:153], v[190:193], v[108:111]
	v_mfma_f32_16x16x32_bf16 v[100:103], v[142:145], v[198:201], v[100:103]
	v_mfma_f32_16x16x32_bf16 v[92:95], v[150:153], v[198:201], v[92:95]
	v_mfma_f32_16x16x32_bf16 v[84:87], v[142:145], v[206:209], v[84:87]
	v_mfma_f32_16x16x32_bf16 v[76:79], v[150:153], v[206:209], v[76:79]
	v_mfma_f32_16x16x32_bf16 v[124:127], v[146:149], v[186:189], v[124:127]
	v_mfma_f32_16x16x32_bf16 v[120:123], v[154:157], v[186:189], v[120:123]
	v_mfma_f32_16x16x32_bf16 v[116:119], v[146:149], v[194:197], v[116:119]
	v_mfma_f32_16x16x32_bf16 v[108:111], v[154:157], v[194:197], v[108:111]
	v_mfma_f32_16x16x32_bf16 v[100:103], v[146:149], v[202:205], v[100:103]
	v_mfma_f32_16x16x32_bf16 v[92:95], v[154:157], v[202:205], v[92:95]
	v_mfma_f32_16x16x32_bf16 v[84:87], v[146:149], v[210:213], v[84:87]
	v_mfma_f32_16x16x32_bf16 v[76:79], v[154:157], v[210:213], v[76:79]
	v_mfma_f32_16x16x32_bf16 v[112:115], v[164:167], v[180:183], v[112:115]
	v_mfma_f32_16x16x32_bf16 v[104:107], v[172:175], v[180:183], v[104:107]
	v_mfma_f32_16x16x32_bf16 v[96:99], v[164:167], v[190:193], v[96:99]
	v_mfma_f32_16x16x32_bf16 v[88:91], v[172:175], v[190:193], v[88:91]
	v_mfma_f32_16x16x32_bf16 v[80:83], v[164:167], v[198:201], v[80:83]
	v_mfma_f32_16x16x32_bf16 v[72:75], v[172:175], v[198:201], v[72:75]
	v_mfma_f32_16x16x32_bf16 v[68:71], v[164:167], v[206:209], v[68:71]
	v_mfma_f32_16x16x32_bf16 v[64:67], v[172:175], v[206:209], v[64:67]
	v_mfma_f32_16x16x32_bf16 v[112:115], v[168:171], v[186:189], v[112:115]
	v_mfma_f32_16x16x32_bf16 v[104:107], v[176:179], v[186:189], v[104:107]
	v_mfma_f32_16x16x32_bf16 v[96:99], v[168:171], v[194:197], v[96:99]
	v_mfma_f32_16x16x32_bf16 v[88:91], v[176:179], v[194:197], v[88:91]
	v_mfma_f32_16x16x32_bf16 v[80:83], v[168:171], v[202:205], v[80:83]
	v_mfma_f32_16x16x32_bf16 v[72:75], v[176:179], v[202:205], v[72:75]
	v_mfma_f32_16x16x32_bf16 v[68:71], v[168:171], v[210:213], v[68:71]
	v_mfma_f32_16x16x32_bf16 v[64:67], v[176:179], v[210:213], v[64:67]
	s_setprio 0
	s_barrier
	s_add_i32 s56, s63, s24
	v_lshl_add_u64 v[214:215], v[214:215], 0, s[8:9]
	s_mov_b32 m0, s56
	ds_read_b128 v[180:183], v162 offset:49152
	ds_read_b128 v[186:189], v162 offset:50176
	ds_read_b128 v[190:193], v162 offset:51200
	ds_read_b128 v[194:197], v162 offset:52224
	ds_read_b128 v[198:201], v162 offset:53248
	ds_read_b128 v[202:205], v162 offset:54272
	ds_read_b128 v[206:209], v162 offset:55296
	ds_read_b128 v[210:213], v162 offset:56320
	global_load_lds_dwordx4 v[214:215], off
	s_add_i32 m0, s56, 0x2000
	s_add_u32 s54, s54, 0x40080
	v_lshl_add_u64 v[214:215], v[216:217], 0, s[8:9]
	s_addc_u32 s55, s55, 0
	s_add_i32 s56, s64, s24
	global_load_lds_dwordx4 v[214:215], off
	v_lshl_add_u64 v[214:215], s[54:55], 0, v[130:131]
	s_mov_b32 m0, s56
	s_nop 0
	global_load_lds_dwordx4 v[214:215], off
	v_lshl_add_u64 v[214:215], s[54:55], 0, v[134:135]
	s_add_i32 m0, s56, 0x2000
	s_nop 0
	global_load_lds_dwordx4 v[214:215], off
	v_lshl_add_u64 v[214:215], v[218:219], 0, s[8:9]
	s_mov_b32 m0, s35
	s_nop 0
	global_load_lds_dwordx4 v[214:215], off
	v_lshl_add_u64 v[214:215], v[220:221], 0, s[8:9]
	s_mov_b32 m0, s39
	s_nop 0
	global_load_lds_dwordx4 v[214:215], off
	s_waitcnt vmcnt(8)
	s_waitcnt lgkmcnt(0)
	s_barrier
	s_setprio 1
	s_waitcnt lgkmcnt(0)
	v_mfma_f32_16x16x32_bf16 v[60:63], v[142:145], v[180:183], v[60:63]
	v_mfma_f32_16x16x32_bf16 v[56:59], v[150:153], v[180:183], v[56:59]
	v_mfma_f32_16x16x32_bf16 v[52:55], v[142:145], v[190:193], v[52:55]
	v_mfma_f32_16x16x32_bf16 v[48:51], v[150:153], v[190:193], v[48:51]
	v_mfma_f32_16x16x32_bf16 v[36:39], v[142:145], v[198:201], v[36:39]
	v_mfma_f32_16x16x32_bf16 v[32:35], v[150:153], v[198:201], v[32:35]
	v_mfma_f32_16x16x32_bf16 v[20:23], v[142:145], v[206:209], v[20:23]
	v_mfma_f32_16x16x32_bf16 v[16:19], v[150:153], v[206:209], v[16:19]
	v_mfma_f32_16x16x32_bf16 v[60:63], v[146:149], v[186:189], v[60:63]
	v_mfma_f32_16x16x32_bf16 v[56:59], v[154:157], v[186:189], v[56:59]
	v_mfma_f32_16x16x32_bf16 v[52:55], v[146:149], v[194:197], v[52:55]
	v_mfma_f32_16x16x32_bf16 v[48:51], v[154:157], v[194:197], v[48:51]
	v_mfma_f32_16x16x32_bf16 v[36:39], v[146:149], v[202:205], v[36:39]
	v_mfma_f32_16x16x32_bf16 v[32:35], v[154:157], v[202:205], v[32:35]
	v_mfma_f32_16x16x32_bf16 v[20:23], v[146:149], v[210:213], v[20:23]
	v_mfma_f32_16x16x32_bf16 v[16:19], v[154:157], v[210:213], v[16:19]
	v_mfma_f32_16x16x32_bf16 v[44:47], v[164:167], v[180:183], v[44:47]
	v_mfma_f32_16x16x32_bf16 v[40:43], v[172:175], v[180:183], v[40:43]
	v_mfma_f32_16x16x32_bf16 v[28:31], v[164:167], v[190:193], v[28:31]
	v_mfma_f32_16x16x32_bf16 v[24:27], v[172:175], v[190:193], v[24:27]
	v_mfma_f32_16x16x32_bf16 v[12:15], v[164:167], v[198:201], v[12:15]
	v_mfma_f32_16x16x32_bf16 v[8:11], v[172:175], v[198:201], v[8:11]
	v_mfma_f32_16x16x32_bf16 v[4:7], v[164:167], v[206:209], v[4:7]
	v_mfma_f32_16x16x32_bf16 v[0:3], v[172:175], v[206:209], v[0:3]
	v_mfma_f32_16x16x32_bf16 v[44:47], v[168:171], v[186:189], v[44:47]
	v_mfma_f32_16x16x32_bf16 v[40:43], v[176:179], v[186:189], v[40:43]
	v_mfma_f32_16x16x32_bf16 v[28:31], v[168:171], v[194:197], v[28:31]
	v_mfma_f32_16x16x32_bf16 v[24:27], v[176:179], v[194:197], v[24:27]
	v_mfma_f32_16x16x32_bf16 v[12:15], v[168:171], v[202:205], v[12:15]
	v_mfma_f32_16x16x32_bf16 v[8:11], v[176:179], v[202:205], v[8:11]
	v_mfma_f32_16x16x32_bf16 v[4:7], v[168:171], v[210:213], v[4:7]
	v_mfma_f32_16x16x32_bf16 v[0:3], v[176:179], v[210:213], v[0:3]
	s_setprio 0
	s_barrier
	s_add_i32 s62, s62, 2
	s_add_u32 s52, s52, 0x100
	s_addc_u32 s53, s53, 0
	s_add_u32 s58, s58, 0x100
	s_addc_u32 s59, s59, 0
	s_cmp_gt_u32 s62, 13
	s_cbranch_scc0 .LBB0_105
	s_and_b64 vcc, exec, s[36:37]
	s_cbranch_vccz .LBB0_108
	s_barrier

.LBB0_344:
	ds_read_b128 v[152:155], v182
	ds_read_b128 v[156:159], v182 offset:1024
	ds_read_b128 v[144:147], v182 offset:2048
	ds_read_b128 v[148:151], v182 offset:3072
	ds_read_b128 v[136:139], v183
	ds_read_b128 v[140:143], v183 offset:1024
	ds_read_b128 v[128:131], v183 offset:2048
	ds_read_b128 v[132:135], v183 offset:3072
	s_add_u32 s54, s52, 0xfffe0080
	s_addc_u32 s55, s53, -1
	s_cmp_eq_u32 s58, 4
	s_cselect_b32 s57, s49, s55
	s_cselect_b32 s56, s48, s54
	s_cselect_b32 s55, s51, s47
	s_cselect_b32 s54, s50, s39
	v_lshl_add_u64 v[210:211], s[52:53], 0, v[168:169]
	s_add_i32 m0, s25, 0xc000
	ds_read_b128 v[172:175], v184
	ds_read_b128 v[176:179], v184 offset:1024
	ds_read_b128 v[186:189], v184 offset:2048
	ds_read_b128 v[190:193], v184 offset:3072
	ds_read_b128 v[194:197], v184 offset:4096
	ds_read_b128 v[198:201], v184 offset:5120
	ds_read_b128 v[202:205], v184 offset:6144
	ds_read_b128 v[206:209], v184 offset:7168
	global_load_lds_dwordx4 v[210:211], off
	v_lshl_add_u64 v[210:211], s[52:53], 0, v[170:171]
	s_add_i32 m0, s25, 0xe000
	s_nop 0
	global_load_lds_dwordx4 v[210:211], off
	s_waitcnt vmcnt(8)
	s_waitcnt lgkmcnt(0)
	s_barrier
	s_setprio 1
	s_waitcnt lgkmcnt(0)
	v_mfma_f32_16x16x128_f8f6f4 v[124:127], v[152:159], v[172:179], v[124:127]
	v_mfma_f32_16x16x128_f8f6f4 v[120:123], v[144:151], v[172:179], v[120:123]
	v_mfma_f32_16x16x128_f8f6f4 v[108:111], v[152:159], v[186:193], v[108:111]
	v_mfma_f32_16x16x128_f8f6f4 v[104:107], v[144:151], v[186:193], v[104:107]
	v_mfma_f32_16x16x128_f8f6f4 v[92:95], v[152:159], v[194:201], v[92:95]
	v_mfma_f32_16x16x128_f8f6f4 v[88:91], v[144:151], v[194:201], v[88:91]
	v_mfma_f32_16x16x128_f8f6f4 v[76:79], v[152:159], v[202:209], v[76:79]
	v_mfma_f32_16x16x128_f8f6f4 v[72:75], v[144:151], v[202:209], v[72:75]
	v_mfma_f32_16x16x128_f8f6f4 v[116:119], v[136:143], v[172:179], v[116:119]
	v_mfma_f32_16x16x128_f8f6f4 v[112:115], v[128:135], v[172:179], v[112:115]
	v_mfma_f32_16x16x128_f8f6f4 v[100:103], v[136:143], v[186:193], v[100:103]
	v_mfma_f32_16x16x128_f8f6f4 v[96:99], v[128:135], v[186:193], v[96:99]
	v_mfma_f32_16x16x128_f8f6f4 v[84:87], v[136:143], v[194:201], v[84:87]
	v_mfma_f32_16x16x128_f8f6f4 v[80:83], v[128:135], v[194:201], v[80:83]
	v_mfma_f32_16x16x128_f8f6f4 v[68:71], v[136:143], v[202:209], v[68:71]
	v_mfma_f32_16x16x128_f8f6f4 v[64:67], v[128:135], v[202:209], v[64:67]
	s_setprio 0
	s_barrier
	s_add_i32 s59, s35, s24
	v_lshl_add_u64 v[172:173], s[54:55], 0, v[164:165]
	s_mov_b32 m0, s59
	ds_read_b128 v[186:189], v184 offset:16384
	ds_read_b128 v[190:193], v184 offset:17408
	ds_read_b128 v[194:197], v184 offset:18432
	ds_read_b128 v[198:201], v184 offset:19456
	ds_read_b128 v[202:205], v184 offset:20480
	ds_read_b128 v[206:209], v184 offset:21504
	ds_read_b128 v[210:213], v184 offset:22528
	ds_read_b128 v[214:217], v184 offset:23552
	global_load_lds_dwordx4 v[172:173], off
	s_add_i32 m0, s59, 0x2000
	s_add_u32 s60, s54, 0x20000
	v_lshl_add_u64 v[174:175], s[54:55], 0, v[160:161]
	s_addc_u32 s61, s55, 0
	s_add_i32 s59, s37, s24
	global_load_lds_dwordx4 v[174:175], off
	v_lshl_add_u64 v[176:177], s[60:61], 0, v[164:165]
	s_mov_b32 m0, s59
	v_lshl_add_u64 v[178:179], s[56:57], 0, v[162:163]
	global_load_lds_dwordx4 v[176:177], off
	v_lshl_add_u64 v[176:177], s[60:61], 0, v[160:161]
	s_add_i32 m0, s59, 0x2000
	s_nop 0
	global_load_lds_dwordx4 v[176:177], off
	v_lshl_add_u64 v[176:177], s[56:57], 0, v[166:167]
	s_mov_b32 m0, s25
	s_nop 0
	global_load_lds_dwordx4 v[176:177], off
	s_mov_b32 m0, s26
	s_nop 0
	global_load_lds_dwordx4 v[178:179], off
	s_waitcnt vmcnt(8)
	s_waitcnt lgkmcnt(0)
	s_barrier
	s_setprio 1
	s_waitcnt lgkmcnt(0)
	v_mfma_f32_16x16x128_f8f6f4 v[60:63], v[152:159], v[186:193], v[60:63]
	v_mfma_f32_16x16x128_f8f6f4 v[56:59], v[144:151], v[186:193], v[56:59]
	v_mfma_f32_16x16x128_f8f6f4 v[44:47], v[152:159], v[194:201], v[44:47]
	v_mfma_f32_16x16x128_f8f6f4 v[40:43], v[144:151], v[194:201], v[40:43]
	v_mfma_f32_16x16x128_f8f6f4 v[28:31], v[152:159], v[202:209], v[28:31]
	v_mfma_f32_16x16x128_f8f6f4 v[24:27], v[144:151], v[202:209], v[24:27]
	v_mfma_f32_16x16x128_f8f6f4 v[12:15], v[152:159], v[210:217], v[12:15]
	v_mfma_f32_16x16x128_f8f6f4 v[8:11], v[144:151], v[210:217], v[8:11]
	v_mfma_f32_16x16x128_f8f6f4 v[52:55], v[136:143], v[186:193], v[52:55]
	v_mfma_f32_16x16x128_f8f6f4 v[48:51], v[128:135], v[186:193], v[48:51]
	v_mfma_f32_16x16x128_f8f6f4 v[36:39], v[136:143], v[194:201], v[36:39]
	v_mfma_f32_16x16x128_f8f6f4 v[32:35], v[128:135], v[194:201], v[32:35]
	v_mfma_f32_16x16x128_f8f6f4 v[20:23], v[136:143], v[202:209], v[20:23]
	v_mfma_f32_16x16x128_f8f6f4 v[16:19], v[128:135], v[202:209], v[16:19]
	v_mfma_f32_16x16x128_f8f6f4 v[4:7], v[136:143], v[210:217], v[4:7]
	v_mfma_f32_16x16x128_f8f6f4 v[0:3], v[128:135], v[210:217], v[0:3]
	s_setprio 0
	s_barrier
	s_add_i32 s59, 0, 0x18000
	v_add_u32_e32 v128, s59, v181
	s_add_i32 s60, 0, 0x1c000
	ds_read_b128 v[152:155], v128
	ds_read_b128 v[156:159], v128 offset:1024
	ds_read_b128 v[144:147], v128 offset:2048
	ds_read_b128 v[148:151], v128 offset:3072
	v_add_u32_e32 v128, s60, v181
	ds_read_b128 v[136:139], v128
	ds_read_b128 v[140:143], v128 offset:1024
	ds_read_b128 v[132:135], v128 offset:3072
	ds_read_b128 v[128:131], v128 offset:2048
	s_add_u32 s56, s56, 0x20000
	s_addc_u32 s57, s57, 0
	s_mov_b32 m0, s27
	v_lshl_add_u64 v[218:219], s[56:57], 0, v[166:167]
	ds_read_b128 v[186:189], v184 offset:32768
	ds_read_b128 v[190:193], v184 offset:33792
	ds_read_b128 v[194:197], v184 offset:34816
	ds_read_b128 v[198:201], v184 offset:35840
	ds_read_b128 v[202:205], v184 offset:36864
	ds_read_b128 v[206:209], v184 offset:37888
	ds_read_b128 v[210:213], v184 offset:38912
	ds_read_b128 v[214:217], v184 offset:39936
	global_load_lds_dwordx4 v[218:219], off
	v_lshl_add_u64 v[218:219], s[56:57], 0, v[162:163]
	s_mov_b32 m0, s28
	s_nop 0
	global_load_lds_dwordx4 v[218:219], off
	s_waitcnt vmcnt(8)
	s_waitcnt lgkmcnt(0)
	s_barrier
	s_setprio 1
	s_waitcnt lgkmcnt(0)
	v_mfma_f32_16x16x128_f8f6f4 v[124:127], v[152:159], v[186:193], v[124:127]
	v_mfma_f32_16x16x128_f8f6f4 v[120:123], v[144:151], v[186:193], v[120:123]
	v_mfma_f32_16x16x128_f8f6f4 v[108:111], v[152:159], v[194:201], v[108:111]
	v_mfma_f32_16x16x128_f8f6f4 v[104:107], v[144:151], v[194:201], v[104:107]
	v_mfma_f32_16x16x128_f8f6f4 v[92:95], v[152:159], v[202:209], v[92:95]
	v_mfma_f32_16x16x128_f8f6f4 v[88:91], v[144:151], v[202:209], v[88:91]
	v_mfma_f32_16x16x128_f8f6f4 v[76:79], v[152:159], v[210:217], v[76:79]
	v_mfma_f32_16x16x128_f8f6f4 v[72:75], v[144:151], v[210:217], v[72:75]
	v_mfma_f32_16x16x128_f8f6f4 v[116:119], v[136:143], v[186:193], v[116:119]
	v_mfma_f32_16x16x128_f8f6f4 v[112:115], v[128:135], v[186:193], v[112:115]
	v_mfma_f32_16x16x128_f8f6f4 v[100:103], v[136:143], v[194:201], v[100:103]
	v_mfma_f32_16x16x128_f8f6f4 v[96:99], v[128:135], v[194:201], v[96:99]
	v_mfma_f32_16x16x128_f8f6f4 v[84:87], v[136:143], v[202:209], v[84:87]
	v_mfma_f32_16x16x128_f8f6f4 v[80:83], v[128:135], v[202:209], v[80:83]
	v_mfma_f32_16x16x128_f8f6f4 v[68:71], v[136:143], v[210:217], v[68:71]
	v_mfma_f32_16x16x128_f8f6f4 v[64:67], v[128:135], v[210:217], v[64:67]
	s_setprio 0
	s_barrier
	s_add_i32 s56, s59, s24
	v_lshl_add_u64 v[172:173], v[172:173], 0, s[6:7]
	s_mov_b32 m0, s56
	ds_read_b128 v[186:189], v184 offset:49152
	ds_read_b128 v[190:193], v184 offset:50176
	ds_read_b128 v[194:197], v184 offset:51200
	ds_read_b128 v[198:201], v184 offset:52224
	ds_read_b128 v[202:205], v184 offset:53248
	ds_read_b128 v[206:209], v184 offset:54272
	ds_read_b128 v[210:213], v184 offset:55296
	ds_read_b128 v[214:217], v184 offset:56320
	global_load_lds_dwordx4 v[172:173], off
	s_add_i32 m0, s56, 0x2000
	s_add_u32 s54, s54, 0x20080
	v_lshl_add_u64 v[172:173], v[174:175], 0, s[6:7]
	s_addc_u32 s55, s55, 0
	s_add_i32 s56, s60, s24
	global_load_lds_dwordx4 v[172:173], off
	v_lshl_add_u64 v[172:173], s[54:55], 0, v[164:165]
	s_mov_b32 m0, s56
	s_nop 0
	global_load_lds_dwordx4 v[172:173], off
	v_lshl_add_u64 v[172:173], s[54:55], 0, v[160:161]
	s_add_i32 m0, s56, 0x2000
	s_nop 0
	global_load_lds_dwordx4 v[172:173], off
	v_lshl_add_u64 v[172:173], v[176:177], 0, s[6:7]
	s_mov_b32 m0, s33
	s_nop 0
	global_load_lds_dwordx4 v[172:173], off
	v_lshl_add_u64 v[172:173], v[178:179], 0, s[6:7]
	s_mov_b32 m0, s34
	s_nop 0
	global_load_lds_dwordx4 v[172:173], off
	s_waitcnt vmcnt(8)
	s_waitcnt lgkmcnt(0)
	s_barrier
	s_setprio 1
	s_waitcnt lgkmcnt(0)
	v_mfma_f32_16x16x128_f8f6f4 v[60:63], v[152:159], v[186:193], v[60:63]
	v_mfma_f32_16x16x128_f8f6f4 v[56:59], v[144:151], v[186:193], v[56:59]
	v_mfma_f32_16x16x128_f8f6f4 v[44:47], v[152:159], v[194:201], v[44:47]
	v_mfma_f32_16x16x128_f8f6f4 v[40:43], v[144:151], v[194:201], v[40:43]
	v_mfma_f32_16x16x128_f8f6f4 v[28:31], v[152:159], v[202:209], v[28:31]
	v_mfma_f32_16x16x128_f8f6f4 v[24:27], v[144:151], v[202:209], v[24:27]
	v_mfma_f32_16x16x128_f8f6f4 v[12:15], v[152:159], v[210:217], v[12:15]
	v_mfma_f32_16x16x128_f8f6f4 v[8:11], v[144:151], v[210:217], v[8:11]
	v_mfma_f32_16x16x128_f8f6f4 v[52:55], v[136:143], v[186:193], v[52:55]
	v_mfma_f32_16x16x128_f8f6f4 v[48:51], v[128:135], v[186:193], v[48:51]
	v_mfma_f32_16x16x128_f8f6f4 v[36:39], v[136:143], v[194:201], v[36:39]
	v_mfma_f32_16x16x128_f8f6f4 v[32:35], v[128:135], v[194:201], v[32:35]
	v_mfma_f32_16x16x128_f8f6f4 v[20:23], v[136:143], v[202:209], v[20:23]
	v_mfma_f32_16x16x128_f8f6f4 v[16:19], v[128:135], v[202:209], v[16:19]
	v_mfma_f32_16x16x128_f8f6f4 v[4:7], v[136:143], v[210:217], v[4:7]
	v_mfma_f32_16x16x128_f8f6f4 v[0:3], v[128:135], v[210:217], v[0:3]
	s_setprio 0
	s_barrier
	s_add_i32 s58, s58, 2
	s_add_u32 s52, s52, 0x100
	s_addc_u32 s53, s53, 0
	s_add_u32 s39, s39, 0x100
	s_addc_u32 s47, s47, 0
	s_cmp_gt_u32 s58, 5
	s_cbranch_scc0 .LBB0_344
	s_and_b64 vcc, exec, s[8:9]
	v_readlane_b32 s58, v247, 26
	v_readlane_b32 s59, v247, 27
	s_cbranch_vccz .LBB0_347
	s_barrier

.LBB0_648:
	v_add_u32_e32 v152, s51, v159
	v_add_u32_e32 v156, s52, v159
	ds_read_b128 v[140:143], v152
	ds_read_b128 v[144:147], v152 offset:1024
	ds_read_b128 v[148:151], v152 offset:2048
	ds_read_b128 v[152:155], v152 offset:3072
	ds_read_b128 v[162:165], v156
	ds_read_b128 v[166:169], v156 offset:1024
	ds_read_b128 v[170:173], v156 offset:2048
	ds_read_b128 v[174:177], v156 offset:3072
	s_add_u32 s36, s34, 0xfffc0080
	s_addc_u32 s37, s35, -1
	s_cmp_eq_u32 s58, 12
	s_cselect_b32 s39, s29, s37
	s_cselect_b32 s38, s28, s36
	s_cselect_b32 s37, s31, s57
	s_cselect_b32 s36, s30, s21
	v_lshl_add_u64 v[156:157], s[34:35], 0, v[136:137]
	s_add_i32 m0, s42, 0xc000
	ds_read_b128 v[178:181], v160
	ds_read_b128 v[186:189], v160 offset:1024
	ds_read_b128 v[190:193], v160 offset:2048
	ds_read_b128 v[194:197], v160 offset:3072
	ds_read_b128 v[198:201], v160 offset:4096
	ds_read_b128 v[202:205], v160 offset:5120
	ds_read_b128 v[206:209], v160 offset:6144
	ds_read_b128 v[210:213], v160 offset:7168
	global_load_lds_dwordx4 v[156:157], off
	v_lshl_add_u64 v[156:157], s[34:35], 0, v[138:139]
	s_add_i32 m0, s42, 0xe000
	s_nop 0
	global_load_lds_dwordx4 v[156:157], off
	s_waitcnt vmcnt(8)
	s_waitcnt lgkmcnt(0)
	s_barrier
	s_setprio 1
	s_waitcnt lgkmcnt(0)
	v_mfma_f32_16x16x32_bf16 v[124:127], v[140:143], v[178:181], v[124:127]
	v_mfma_f32_16x16x32_bf16 v[120:123], v[148:151], v[178:181], v[120:123]
	v_mfma_f32_16x16x32_bf16 v[116:119], v[140:143], v[190:193], v[116:119]
	v_mfma_f32_16x16x32_bf16 v[112:115], v[148:151], v[190:193], v[112:115]
	v_mfma_f32_16x16x32_bf16 v[108:111], v[140:143], v[198:201], v[108:111]
	v_mfma_f32_16x16x32_bf16 v[104:107], v[148:151], v[198:201], v[104:107]
	v_mfma_f32_16x16x32_bf16 v[100:103], v[140:143], v[206:209], v[100:103]
	v_mfma_f32_16x16x32_bf16 v[96:99], v[148:151], v[206:209], v[96:99]
	v_mfma_f32_16x16x32_bf16 v[124:127], v[144:147], v[186:189], v[124:127]
	v_mfma_f32_16x16x32_bf16 v[120:123], v[152:155], v[186:189], v[120:123]
	v_mfma_f32_16x16x32_bf16 v[116:119], v[144:147], v[194:197], v[116:119]
	v_mfma_f32_16x16x32_bf16 v[112:115], v[152:155], v[194:197], v[112:115]
	v_mfma_f32_16x16x32_bf16 v[108:111], v[144:147], v[202:205], v[108:111]
	v_mfma_f32_16x16x32_bf16 v[104:107], v[152:155], v[202:205], v[104:107]
	v_mfma_f32_16x16x32_bf16 v[100:103], v[144:147], v[210:213], v[100:103]
	v_mfma_f32_16x16x32_bf16 v[96:99], v[152:155], v[210:213], v[96:99]
	v_mfma_f32_16x16x32_bf16 v[92:95], v[162:165], v[178:181], v[92:95]
	v_mfma_f32_16x16x32_bf16 v[88:91], v[170:173], v[178:181], v[88:91]
	v_mfma_f32_16x16x32_bf16 v[84:87], v[162:165], v[190:193], v[84:87]
	v_mfma_f32_16x16x32_bf16 v[80:83], v[170:173], v[190:193], v[80:83]
	v_mfma_f32_16x16x32_bf16 v[76:79], v[162:165], v[198:201], v[76:79]
	v_mfma_f32_16x16x32_bf16 v[72:75], v[170:173], v[198:201], v[72:75]
	v_mfma_f32_16x16x32_bf16 v[68:71], v[162:165], v[206:209], v[68:71]
	v_mfma_f32_16x16x32_bf16 v[64:67], v[170:173], v[206:209], v[64:67]
	v_mfma_f32_16x16x32_bf16 v[92:95], v[166:169], v[186:189], v[92:95]
	v_mfma_f32_16x16x32_bf16 v[88:91], v[174:177], v[186:189], v[88:91]
	v_mfma_f32_16x16x32_bf16 v[84:87], v[166:169], v[194:197], v[84:87]
	v_mfma_f32_16x16x32_bf16 v[80:83], v[174:177], v[194:197], v[80:83]
	v_mfma_f32_16x16x32_bf16 v[76:79], v[166:169], v[202:205], v[76:79]
	v_mfma_f32_16x16x32_bf16 v[72:75], v[174:177], v[202:205], v[72:75]
	v_mfma_f32_16x16x32_bf16 v[68:71], v[166:169], v[210:213], v[68:71]
	v_mfma_f32_16x16x32_bf16 v[64:67], v[174:177], v[210:213], v[64:67]
	s_setprio 0
	s_barrier
	s_add_i32 s59, s51, s41
	v_lshl_add_u64 v[156:157], s[36:37], 0, v[130:131]
	s_mov_b32 m0, s59
	ds_read_b128 v[178:181], v160 offset:16384
	ds_read_b128 v[186:189], v160 offset:17408
	ds_read_b128 v[190:193], v160 offset:18432
	ds_read_b128 v[194:197], v160 offset:19456
	ds_read_b128 v[198:201], v160 offset:20480
	ds_read_b128 v[202:205], v160 offset:21504
	ds_read_b128 v[206:209], v160 offset:22528
	ds_read_b128 v[210:213], v160 offset:23552
	global_load_lds_dwordx4 v[156:157], off
	s_add_i32 m0, s59, 0x2000
	s_add_u32 s60, s36, 0x40000
	v_lshl_add_u64 v[182:183], s[36:37], 0, v[134:135]
	s_addc_u32 s61, s37, 0
	s_add_i32 s59, s52, s41
	global_load_lds_dwordx4 v[182:183], off
	v_lshl_add_u64 v[214:215], s[60:61], 0, v[130:131]
	s_mov_b32 m0, s59
	v_lshl_add_u64 v[216:217], s[38:39], 0, v[132:133]
	global_load_lds_dwordx4 v[214:215], off
	v_lshl_add_u64 v[214:215], s[60:61], 0, v[134:135]
	s_add_i32 m0, s59, 0x2000
	s_nop 0
	global_load_lds_dwordx4 v[214:215], off
	v_lshl_add_u64 v[214:215], s[38:39], 0, v[128:129]
	s_mov_b32 m0, s42
	s_nop 0
	global_load_lds_dwordx4 v[214:215], off
	s_mov_b32 m0, s43
	s_nop 0
	global_load_lds_dwordx4 v[216:217], off
	s_waitcnt vmcnt(8)
	s_waitcnt lgkmcnt(0)
	s_barrier
	s_setprio 1
	s_waitcnt lgkmcnt(0)
	v_mfma_f32_16x16x32_bf16 v[60:63], v[140:143], v[178:181], v[60:63]
	v_mfma_f32_16x16x32_bf16 v[56:59], v[148:151], v[178:181], v[56:59]
	v_mfma_f32_16x16x32_bf16 v[52:55], v[140:143], v[190:193], v[52:55]
	v_mfma_f32_16x16x32_bf16 v[48:51], v[148:151], v[190:193], v[48:51]
	v_mfma_f32_16x16x32_bf16 v[44:47], v[140:143], v[198:201], v[44:47]
	v_mfma_f32_16x16x32_bf16 v[40:43], v[148:151], v[198:201], v[40:43]
	v_mfma_f32_16x16x32_bf16 v[36:39], v[140:143], v[206:209], v[36:39]
	v_mfma_f32_16x16x32_bf16 v[32:35], v[148:151], v[206:209], v[32:35]
	v_mfma_f32_16x16x32_bf16 v[60:63], v[144:147], v[186:189], v[60:63]
	v_mfma_f32_16x16x32_bf16 v[56:59], v[152:155], v[186:189], v[56:59]
	v_mfma_f32_16x16x32_bf16 v[52:55], v[144:147], v[194:197], v[52:55]
	v_mfma_f32_16x16x32_bf16 v[48:51], v[152:155], v[194:197], v[48:51]
	v_mfma_f32_16x16x32_bf16 v[44:47], v[144:147], v[202:205], v[44:47]
	v_mfma_f32_16x16x32_bf16 v[40:43], v[152:155], v[202:205], v[40:43]
	v_mfma_f32_16x16x32_bf16 v[36:39], v[144:147], v[210:213], v[36:39]
	v_mfma_f32_16x16x32_bf16 v[32:35], v[152:155], v[210:213], v[32:35]
	v_mfma_f32_16x16x32_bf16 v[28:31], v[162:165], v[178:181], v[28:31]
	v_mfma_f32_16x16x32_bf16 v[24:27], v[170:173], v[178:181], v[24:27]
	v_mfma_f32_16x16x32_bf16 v[20:23], v[162:165], v[190:193], v[20:23]
	v_mfma_f32_16x16x32_bf16 v[16:19], v[170:173], v[190:193], v[16:19]
	v_mfma_f32_16x16x32_bf16 v[12:15], v[162:165], v[198:201], v[12:15]
	v_mfma_f32_16x16x32_bf16 v[8:11], v[170:173], v[198:201], v[8:11]
	v_mfma_f32_16x16x32_bf16 v[4:7], v[162:165], v[206:209], v[4:7]
	v_mfma_f32_16x16x32_bf16 v[0:3], v[170:173], v[206:209], v[0:3]
	v_mfma_f32_16x16x32_bf16 v[28:31], v[166:169], v[186:189], v[28:31]
	v_mfma_f32_16x16x32_bf16 v[24:27], v[174:177], v[186:189], v[24:27]
	v_mfma_f32_16x16x32_bf16 v[20:23], v[166:169], v[194:197], v[20:23]
	v_mfma_f32_16x16x32_bf16 v[16:19], v[174:177], v[194:197], v[16:19]
	v_mfma_f32_16x16x32_bf16 v[12:15], v[166:169], v[202:205], v[12:15]
	v_mfma_f32_16x16x32_bf16 v[8:11], v[174:177], v[202:205], v[8:11]
	v_mfma_f32_16x16x32_bf16 v[4:7], v[166:169], v[210:213], v[4:7]
	v_mfma_f32_16x16x32_bf16 v[0:3], v[174:177], v[210:213], v[0:3]
	s_setprio 0
	s_barrier
	s_add_i32 s59, 0, 0x18000
	s_add_i32 s60, 0, 0x1c000
	v_add_u32_e32 v152, s59, v159
	v_add_u32_e32 v161, s60, v159
	ds_read_b128 v[140:143], v152
	ds_read_b128 v[144:147], v152 offset:1024
	ds_read_b128 v[148:151], v152 offset:2048
	ds_read_b128 v[152:155], v152 offset:3072
	ds_read_b128 v[162:165], v161
	ds_read_b128 v[166:169], v161 offset:1024
	ds_read_b128 v[170:173], v161 offset:2048
	ds_read_b128 v[174:177], v161 offset:3072
	s_add_u32 s38, s38, 0x40000
	s_addc_u32 s39, s39, 0
	s_mov_b32 m0, s44
	v_lshl_add_u64 v[218:219], s[38:39], 0, v[128:129]
	ds_read_b128 v[178:181], v160 offset:32768
	ds_read_b128 v[186:189], v160 offset:33792
	ds_read_b128 v[190:193], v160 offset:34816
	ds_read_b128 v[194:197], v160 offset:35840
	ds_read_b128 v[198:201], v160 offset:36864
	ds_read_b128 v[202:205], v160 offset:37888
	ds_read_b128 v[206:209], v160 offset:38912
	ds_read_b128 v[210:213], v160 offset:39936
	global_load_lds_dwordx4 v[218:219], off
	v_lshl_add_u64 v[218:219], s[38:39], 0, v[132:133]
	s_mov_b32 m0, s45
	s_nop 0
	global_load_lds_dwordx4 v[218:219], off
	s_waitcnt vmcnt(8)
	s_waitcnt lgkmcnt(0)
	s_barrier
	s_setprio 1
	s_waitcnt lgkmcnt(0)
	v_mfma_f32_16x16x32_bf16 v[124:127], v[140:143], v[178:181], v[124:127]
	v_mfma_f32_16x16x32_bf16 v[120:123], v[148:151], v[178:181], v[120:123]
	v_mfma_f32_16x16x32_bf16 v[116:119], v[140:143], v[190:193], v[116:119]
	v_mfma_f32_16x16x32_bf16 v[112:115], v[148:151], v[190:193], v[112:115]
	v_mfma_f32_16x16x32_bf16 v[108:111], v[140:143], v[198:201], v[108:111]
	v_mfma_f32_16x16x32_bf16 v[104:107], v[148:151], v[198:201], v[104:107]
	v_mfma_f32_16x16x32_bf16 v[100:103], v[140:143], v[206:209], v[100:103]
	v_mfma_f32_16x16x32_bf16 v[96:99], v[148:151], v[206:209], v[96:99]
	v_mfma_f32_16x16x32_bf16 v[124:127], v[144:147], v[186:189], v[124:127]
	v_mfma_f32_16x16x32_bf16 v[120:123], v[152:155], v[186:189], v[120:123]
	v_mfma_f32_16x16x32_bf16 v[116:119], v[144:147], v[194:197], v[116:119]
	v_mfma_f32_16x16x32_bf16 v[112:115], v[152:155], v[194:197], v[112:115]
	v_mfma_f32_16x16x32_bf16 v[108:111], v[144:147], v[202:205], v[108:111]
	v_mfma_f32_16x16x32_bf16 v[104:107], v[152:155], v[202:205], v[104:107]
	v_mfma_f32_16x16x32_bf16 v[100:103], v[144:147], v[210:213], v[100:103]
	v_mfma_f32_16x16x32_bf16 v[96:99], v[152:155], v[210:213], v[96:99]
	v_mfma_f32_16x16x32_bf16 v[92:95], v[162:165], v[178:181], v[92:95]
	v_mfma_f32_16x16x32_bf16 v[88:91], v[170:173], v[178:181], v[88:91]
	v_mfma_f32_16x16x32_bf16 v[84:87], v[162:165], v[190:193], v[84:87]
	v_mfma_f32_16x16x32_bf16 v[80:83], v[170:173], v[190:193], v[80:83]
	v_mfma_f32_16x16x32_bf16 v[76:79], v[162:165], v[198:201], v[76:79]
	v_mfma_f32_16x16x32_bf16 v[72:75], v[170:173], v[198:201], v[72:75]
	v_mfma_f32_16x16x32_bf16 v[68:71], v[162:165], v[206:209], v[68:71]
	v_mfma_f32_16x16x32_bf16 v[64:67], v[170:173], v[206:209], v[64:67]
	v_mfma_f32_16x16x32_bf16 v[92:95], v[166:169], v[186:189], v[92:95]
	v_mfma_f32_16x16x32_bf16 v[88:91], v[174:177], v[186:189], v[88:91]
	v_mfma_f32_16x16x32_bf16 v[84:87], v[166:169], v[194:197], v[84:87]
	v_mfma_f32_16x16x32_bf16 v[80:83], v[174:177], v[194:197], v[80:83]
	v_mfma_f32_16x16x32_bf16 v[76:79], v[166:169], v[202:205], v[76:79]
	v_mfma_f32_16x16x32_bf16 v[72:75], v[174:177], v[202:205], v[72:75]
	v_mfma_f32_16x16x32_bf16 v[68:71], v[166:169], v[210:213], v[68:71]
	v_mfma_f32_16x16x32_bf16 v[64:67], v[174:177], v[210:213], v[64:67]
	s_setprio 0
	s_barrier
	s_add_i32 s38, s59, s41
	v_lshl_add_u64 v[156:157], v[156:157], 0, s[8:9]
	s_mov_b32 m0, s38
	ds_read_b128 v[178:181], v160 offset:49152
	ds_read_b128 v[186:189], v160 offset:50176
	ds_read_b128 v[190:193], v160 offset:51200
	ds_read_b128 v[194:197], v160 offset:52224
	ds_read_b128 v[198:201], v160 offset:53248
	ds_read_b128 v[202:205], v160 offset:54272
	ds_read_b128 v[206:209], v160 offset:55296
	ds_read_b128 v[210:213], v160 offset:56320
	global_load_lds_dwordx4 v[156:157], off
	s_add_i32 m0, s38, 0x2000
	s_add_u32 s36, s36, 0x40080
	v_lshl_add_u64 v[156:157], v[182:183], 0, s[8:9]
	s_addc_u32 s37, s37, 0
	s_add_i32 s38, s60, s41
	global_load_lds_dwordx4 v[156:157], off
	v_lshl_add_u64 v[156:157], s[36:37], 0, v[130:131]
	s_mov_b32 m0, s38
	s_nop 0
	global_load_lds_dwordx4 v[156:157], off
	v_lshl_add_u64 v[156:157], s[36:37], 0, v[134:135]
	s_add_i32 m0, s38, 0x2000
	s_nop 0
	global_load_lds_dwordx4 v[156:157], off
	v_lshl_add_u64 v[156:157], v[214:215], 0, s[8:9]
	s_mov_b32 m0, s48
	s_nop 0
	global_load_lds_dwordx4 v[156:157], off
	v_lshl_add_u64 v[156:157], v[216:217], 0, s[8:9]
	s_mov_b32 m0, s49
	s_nop 0
	global_load_lds_dwordx4 v[156:157], off
	s_waitcnt vmcnt(8)
	s_waitcnt lgkmcnt(0)
	s_barrier
	s_setprio 1
	s_waitcnt lgkmcnt(0)
	v_mfma_f32_16x16x32_bf16 v[60:63], v[140:143], v[178:181], v[60:63]
	v_mfma_f32_16x16x32_bf16 v[56:59], v[148:151], v[178:181], v[56:59]
	v_mfma_f32_16x16x32_bf16 v[52:55], v[140:143], v[190:193], v[52:55]
	v_mfma_f32_16x16x32_bf16 v[48:51], v[148:151], v[190:193], v[48:51]
	v_mfma_f32_16x16x32_bf16 v[44:47], v[140:143], v[198:201], v[44:47]
	v_mfma_f32_16x16x32_bf16 v[40:43], v[148:151], v[198:201], v[40:43]
	v_mfma_f32_16x16x32_bf16 v[36:39], v[140:143], v[206:209], v[36:39]
	v_mfma_f32_16x16x32_bf16 v[32:35], v[148:151], v[206:209], v[32:35]
	v_mfma_f32_16x16x32_bf16 v[60:63], v[144:147], v[186:189], v[60:63]
	v_mfma_f32_16x16x32_bf16 v[56:59], v[152:155], v[186:189], v[56:59]
	v_mfma_f32_16x16x32_bf16 v[52:55], v[144:147], v[194:197], v[52:55]
	v_mfma_f32_16x16x32_bf16 v[48:51], v[152:155], v[194:197], v[48:51]
	v_mfma_f32_16x16x32_bf16 v[44:47], v[144:147], v[202:205], v[44:47]
	v_mfma_f32_16x16x32_bf16 v[40:43], v[152:155], v[202:205], v[40:43]
	v_mfma_f32_16x16x32_bf16 v[36:39], v[144:147], v[210:213], v[36:39]
	v_mfma_f32_16x16x32_bf16 v[32:35], v[152:155], v[210:213], v[32:35]
	v_mfma_f32_16x16x32_bf16 v[28:31], v[162:165], v[178:181], v[28:31]
	v_mfma_f32_16x16x32_bf16 v[24:27], v[170:173], v[178:181], v[24:27]
	v_mfma_f32_16x16x32_bf16 v[20:23], v[162:165], v[190:193], v[20:23]
	v_mfma_f32_16x16x32_bf16 v[16:19], v[170:173], v[190:193], v[16:19]
	v_mfma_f32_16x16x32_bf16 v[12:15], v[162:165], v[198:201], v[12:15]
	v_mfma_f32_16x16x32_bf16 v[8:11], v[170:173], v[198:201], v[8:11]
	v_mfma_f32_16x16x32_bf16 v[4:7], v[162:165], v[206:209], v[4:7]
	v_mfma_f32_16x16x32_bf16 v[0:3], v[170:173], v[206:209], v[0:3]
	v_mfma_f32_16x16x32_bf16 v[28:31], v[166:169], v[186:189], v[28:31]
	v_mfma_f32_16x16x32_bf16 v[24:27], v[174:177], v[186:189], v[24:27]
	v_mfma_f32_16x16x32_bf16 v[20:23], v[166:169], v[194:197], v[20:23]
	v_mfma_f32_16x16x32_bf16 v[16:19], v[174:177], v[194:197], v[16:19]
	v_mfma_f32_16x16x32_bf16 v[12:15], v[166:169], v[202:205], v[12:15]
	v_mfma_f32_16x16x32_bf16 v[8:11], v[174:177], v[202:205], v[8:11]
	v_mfma_f32_16x16x32_bf16 v[4:7], v[166:169], v[210:213], v[4:7]
	v_mfma_f32_16x16x32_bf16 v[0:3], v[174:177], v[210:213], v[0:3]
	s_setprio 0
	s_barrier
	s_add_i32 s58, s58, 2
	s_add_u32 s34, s34, 0x100
	s_addc_u32 s35, s35, 0
	s_add_u32 s21, s21, 0x100
	s_addc_u32 s57, s57, 0
	s_cmp_gt_u32 s58, 13
	s_cbranch_scc0 .LBB0_648
	s_and_b64 vcc, exec, s[10:11]
	s_cbranch_vccz .LBB0_651
	s_barrier

.LBB0_792:
	ds_read_b128 v[140:143], v146
	ds_read_b128 v[150:153], v146 offset:1024
	ds_read_b128 v[154:157], v146 offset:2048
	ds_read_b128 v[158:161], v146 offset:3072
	ds_read_b128 v[162:165], v147
	ds_read_b128 v[166:169], v147 offset:1024
	ds_read_b128 v[170:173], v147 offset:2048
	ds_read_b128 v[174:177], v147 offset:3072
	s_add_u32 s28, s26, 0xfffc0080
	s_addc_u32 s29, s27, -1
	s_cmp_eq_u32 s52, 12
	s_cselect_b32 s31, s23, s29
	s_cselect_b32 s30, s22, s28
	s_cselect_b32 s29, s25, s51
	s_cselect_b32 s28, s24, s15
	v_lshl_add_u64 v[182:183], s[26:27], 0, v[136:137]
	s_add_i32 m0, s37, 0xc000
	ds_read_b128 v[178:181], v148
	ds_read_b128 v[186:189], v148 offset:1024
	ds_read_b128 v[190:193], v148 offset:2048
	ds_read_b128 v[194:197], v148 offset:3072
	ds_read_b128 v[198:201], v148 offset:4096
	ds_read_b128 v[202:205], v148 offset:5120
	ds_read_b128 v[206:209], v148 offset:6144
	ds_read_b128 v[210:213], v148 offset:7168
	global_load_lds_dwordx4 v[182:183], off
	v_lshl_add_u64 v[182:183], s[26:27], 0, v[138:139]
	s_add_i32 m0, s37, 0xe000
	s_nop 0
	global_load_lds_dwordx4 v[182:183], off
	s_waitcnt vmcnt(8)
	s_waitcnt lgkmcnt(0)
	s_barrier
	s_setprio 1
	s_waitcnt lgkmcnt(0)
	v_mfma_f32_16x16x32_bf16 v[124:127], v[140:143], v[178:181], v[124:127]
	v_mfma_f32_16x16x32_bf16 v[120:123], v[154:157], v[178:181], v[120:123]
	v_mfma_f32_16x16x32_bf16 v[108:111], v[140:143], v[190:193], v[108:111]
	v_mfma_f32_16x16x32_bf16 v[104:107], v[154:157], v[190:193], v[104:107]
	v_mfma_f32_16x16x32_bf16 v[92:95], v[140:143], v[198:201], v[92:95]
	v_mfma_f32_16x16x32_bf16 v[88:91], v[154:157], v[198:201], v[88:91]
	v_mfma_f32_16x16x32_bf16 v[76:79], v[140:143], v[206:209], v[76:79]
	v_mfma_f32_16x16x32_bf16 v[72:75], v[154:157], v[206:209], v[72:75]
	v_mfma_f32_16x16x32_bf16 v[124:127], v[150:153], v[186:189], v[124:127]
	v_mfma_f32_16x16x32_bf16 v[120:123], v[158:161], v[186:189], v[120:123]
	v_mfma_f32_16x16x32_bf16 v[108:111], v[150:153], v[194:197], v[108:111]
	v_mfma_f32_16x16x32_bf16 v[104:107], v[158:161], v[194:197], v[104:107]
	v_mfma_f32_16x16x32_bf16 v[92:95], v[150:153], v[202:205], v[92:95]
	v_mfma_f32_16x16x32_bf16 v[88:91], v[158:161], v[202:205], v[88:91]
	v_mfma_f32_16x16x32_bf16 v[76:79], v[150:153], v[210:213], v[76:79]
	v_mfma_f32_16x16x32_bf16 v[72:75], v[158:161], v[210:213], v[72:75]
	v_mfma_f32_16x16x32_bf16 v[116:119], v[162:165], v[178:181], v[116:119]
	v_mfma_f32_16x16x32_bf16 v[112:115], v[170:173], v[178:181], v[112:115]
	v_mfma_f32_16x16x32_bf16 v[100:103], v[162:165], v[190:193], v[100:103]
	v_mfma_f32_16x16x32_bf16 v[96:99], v[170:173], v[190:193], v[96:99]
	v_mfma_f32_16x16x32_bf16 v[84:87], v[162:165], v[198:201], v[84:87]
	v_mfma_f32_16x16x32_bf16 v[80:83], v[170:173], v[198:201], v[80:83]
	v_mfma_f32_16x16x32_bf16 v[68:71], v[162:165], v[206:209], v[68:71]
	v_mfma_f32_16x16x32_bf16 v[64:67], v[170:173], v[206:209], v[64:67]
	v_mfma_f32_16x16x32_bf16 v[116:119], v[166:169], v[186:189], v[116:119]
	v_mfma_f32_16x16x32_bf16 v[112:115], v[174:177], v[186:189], v[112:115]
	v_mfma_f32_16x16x32_bf16 v[100:103], v[166:169], v[194:197], v[100:103]
	v_mfma_f32_16x16x32_bf16 v[96:99], v[174:177], v[194:197], v[96:99]
	v_mfma_f32_16x16x32_bf16 v[84:87], v[166:169], v[202:205], v[84:87]
	v_mfma_f32_16x16x32_bf16 v[80:83], v[174:177], v[202:205], v[80:83]
	v_mfma_f32_16x16x32_bf16 v[68:71], v[166:169], v[210:213], v[68:71]
	v_mfma_f32_16x16x32_bf16 v[64:67], v[174:177], v[210:213], v[64:67]
	s_setprio 0
	s_barrier
	s_add_i32 s53, s46, s36
	v_lshl_add_u64 v[182:183], s[28:29], 0, v[130:131]
	s_mov_b32 m0, s53
	ds_read_b128 v[178:181], v148 offset:16384
	ds_read_b128 v[186:189], v148 offset:17408
	ds_read_b128 v[190:193], v148 offset:18432
	ds_read_b128 v[194:197], v148 offset:19456
	ds_read_b128 v[198:201], v148 offset:20480
	ds_read_b128 v[202:205], v148 offset:21504
	ds_read_b128 v[206:209], v148 offset:22528
	ds_read_b128 v[210:213], v148 offset:23552
	global_load_lds_dwordx4 v[182:183], off
	s_add_i32 m0, s53, 0x2000
	s_add_u32 s54, s28, 0x40000
	v_lshl_add_u64 v[214:215], s[28:29], 0, v[134:135]
	s_addc_u32 s55, s29, 0
	s_add_i32 s53, s47, s36
	global_load_lds_dwordx4 v[214:215], off
	v_lshl_add_u64 v[216:217], s[54:55], 0, v[130:131]
	s_mov_b32 m0, s53
	v_lshl_add_u64 v[218:219], s[30:31], 0, v[132:133]
	global_load_lds_dwordx4 v[216:217], off
	v_lshl_add_u64 v[216:217], s[54:55], 0, v[134:135]
	s_add_i32 m0, s53, 0x2000
	s_nop 0
	global_load_lds_dwordx4 v[216:217], off
	v_lshl_add_u64 v[216:217], s[30:31], 0, v[128:129]
	s_mov_b32 m0, s37
	s_nop 0
	global_load_lds_dwordx4 v[216:217], off
	s_mov_b32 m0, s38
	s_nop 0
	global_load_lds_dwordx4 v[218:219], off
	s_waitcnt vmcnt(8)
	s_waitcnt lgkmcnt(0)
	s_barrier
	s_setprio 1
	s_waitcnt lgkmcnt(0)
	v_mfma_f32_16x16x32_bf16 v[60:63], v[140:143], v[178:181], v[60:63]
	v_mfma_f32_16x16x32_bf16 v[56:59], v[154:157], v[178:181], v[56:59]
	v_mfma_f32_16x16x32_bf16 v[44:47], v[140:143], v[190:193], v[44:47]
	v_mfma_f32_16x16x32_bf16 v[40:43], v[154:157], v[190:193], v[40:43]
	v_mfma_f32_16x16x32_bf16 v[28:31], v[140:143], v[198:201], v[28:31]
	v_mfma_f32_16x16x32_bf16 v[24:27], v[154:157], v[198:201], v[24:27]
	v_mfma_f32_16x16x32_bf16 v[12:15], v[140:143], v[206:209], v[12:15]
	v_mfma_f32_16x16x32_bf16 v[8:11], v[154:157], v[206:209], v[8:11]
	v_mfma_f32_16x16x32_bf16 v[60:63], v[150:153], v[186:189], v[60:63]
	v_mfma_f32_16x16x32_bf16 v[56:59], v[158:161], v[186:189], v[56:59]
	v_mfma_f32_16x16x32_bf16 v[44:47], v[150:153], v[194:197], v[44:47]
	v_mfma_f32_16x16x32_bf16 v[40:43], v[158:161], v[194:197], v[40:43]
	v_mfma_f32_16x16x32_bf16 v[28:31], v[150:153], v[202:205], v[28:31]
	v_mfma_f32_16x16x32_bf16 v[24:27], v[158:161], v[202:205], v[24:27]
	v_mfma_f32_16x16x32_bf16 v[12:15], v[150:153], v[210:213], v[12:15]
	v_mfma_f32_16x16x32_bf16 v[8:11], v[158:161], v[210:213], v[8:11]
	v_mfma_f32_16x16x32_bf16 v[52:55], v[162:165], v[178:181], v[52:55]
	v_mfma_f32_16x16x32_bf16 v[48:51], v[170:173], v[178:181], v[48:51]
	v_mfma_f32_16x16x32_bf16 v[36:39], v[162:165], v[190:193], v[36:39]
	v_mfma_f32_16x16x32_bf16 v[32:35], v[170:173], v[190:193], v[32:35]
	v_mfma_f32_16x16x32_bf16 v[20:23], v[162:165], v[198:201], v[20:23]
	v_mfma_f32_16x16x32_bf16 v[16:19], v[170:173], v[198:201], v[16:19]
	v_mfma_f32_16x16x32_bf16 v[4:7], v[162:165], v[206:209], v[4:7]
	v_mfma_f32_16x16x32_bf16 v[0:3], v[170:173], v[206:209], v[0:3]
	v_mfma_f32_16x16x32_bf16 v[52:55], v[166:169], v[186:189], v[52:55]
	v_mfma_f32_16x16x32_bf16 v[48:51], v[174:177], v[186:189], v[48:51]
	v_mfma_f32_16x16x32_bf16 v[36:39], v[166:169], v[194:197], v[36:39]
	v_mfma_f32_16x16x32_bf16 v[32:35], v[174:177], v[194:197], v[32:35]
	v_mfma_f32_16x16x32_bf16 v[20:23], v[166:169], v[202:205], v[20:23]
	v_mfma_f32_16x16x32_bf16 v[16:19], v[174:177], v[202:205], v[16:19]
	v_mfma_f32_16x16x32_bf16 v[4:7], v[166:169], v[210:213], v[4:7]
	v_mfma_f32_16x16x32_bf16 v[0:3], v[174:177], v[210:213], v[0:3]
	s_setprio 0
	s_barrier
	s_add_i32 s53, 0, 0x18000
	s_add_i32 s54, 0, 0x1c000
	v_add_u32_e32 v158, s53, v145
	v_add_u32_e32 v174, s54, v145
	ds_read_b128 v[140:143], v158
	ds_read_b128 v[150:153], v158 offset:1024
	ds_read_b128 v[154:157], v158 offset:2048
	ds_read_b128 v[158:161], v158 offset:3072
	ds_read_b128 v[162:165], v174
	ds_read_b128 v[166:169], v174 offset:1024
	ds_read_b128 v[170:173], v174 offset:2048
	ds_read_b128 v[174:177], v174 offset:3072
	s_add_u32 s30, s30, 0x40000
	s_addc_u32 s31, s31, 0
	s_mov_b32 m0, s39
	v_lshl_add_u64 v[220:221], s[30:31], 0, v[128:129]
	ds_read_b128 v[178:181], v148 offset:32768
	ds_read_b128 v[186:189], v148 offset:33792
	ds_read_b128 v[190:193], v148 offset:34816
	ds_read_b128 v[194:197], v148 offset:35840
	ds_read_b128 v[198:201], v148 offset:36864
	ds_read_b128 v[202:205], v148 offset:37888
	ds_read_b128 v[206:209], v148 offset:38912
	ds_read_b128 v[210:213], v148 offset:39936
	global_load_lds_dwordx4 v[220:221], off
	v_lshl_add_u64 v[220:221], s[30:31], 0, v[132:133]
	s_mov_b32 m0, s40
	s_nop 0
	global_load_lds_dwordx4 v[220:221], off
	s_waitcnt vmcnt(8)
	s_waitcnt lgkmcnt(0)
	s_barrier
	s_setprio 1
	s_waitcnt lgkmcnt(0)
	v_mfma_f32_16x16x32_bf16 v[124:127], v[140:143], v[178:181], v[124:127]
	v_mfma_f32_16x16x32_bf16 v[120:123], v[154:157], v[178:181], v[120:123]
	v_mfma_f32_16x16x32_bf16 v[108:111], v[140:143], v[190:193], v[108:111]
	v_mfma_f32_16x16x32_bf16 v[104:107], v[154:157], v[190:193], v[104:107]
	v_mfma_f32_16x16x32_bf16 v[92:95], v[140:143], v[198:201], v[92:95]
	v_mfma_f32_16x16x32_bf16 v[88:91], v[154:157], v[198:201], v[88:91]
	v_mfma_f32_16x16x32_bf16 v[76:79], v[140:143], v[206:209], v[76:79]
	v_mfma_f32_16x16x32_bf16 v[72:75], v[154:157], v[206:209], v[72:75]
	v_mfma_f32_16x16x32_bf16 v[124:127], v[150:153], v[186:189], v[124:127]
	v_mfma_f32_16x16x32_bf16 v[120:123], v[158:161], v[186:189], v[120:123]
	v_mfma_f32_16x16x32_bf16 v[108:111], v[150:153], v[194:197], v[108:111]
	v_mfma_f32_16x16x32_bf16 v[104:107], v[158:161], v[194:197], v[104:107]
	v_mfma_f32_16x16x32_bf16 v[92:95], v[150:153], v[202:205], v[92:95]
	v_mfma_f32_16x16x32_bf16 v[88:91], v[158:161], v[202:205], v[88:91]
	v_mfma_f32_16x16x32_bf16 v[76:79], v[150:153], v[210:213], v[76:79]
	v_mfma_f32_16x16x32_bf16 v[72:75], v[158:161], v[210:213], v[72:75]
	v_mfma_f32_16x16x32_bf16 v[116:119], v[162:165], v[178:181], v[116:119]
	v_mfma_f32_16x16x32_bf16 v[112:115], v[170:173], v[178:181], v[112:115]
	v_mfma_f32_16x16x32_bf16 v[100:103], v[162:165], v[190:193], v[100:103]
	v_mfma_f32_16x16x32_bf16 v[96:99], v[170:173], v[190:193], v[96:99]
	v_mfma_f32_16x16x32_bf16 v[84:87], v[162:165], v[198:201], v[84:87]
	v_mfma_f32_16x16x32_bf16 v[80:83], v[170:173], v[198:201], v[80:83]
	v_mfma_f32_16x16x32_bf16 v[68:71], v[162:165], v[206:209], v[68:71]
	v_mfma_f32_16x16x32_bf16 v[64:67], v[170:173], v[206:209], v[64:67]
	v_mfma_f32_16x16x32_bf16 v[116:119], v[166:169], v[186:189], v[116:119]
	v_mfma_f32_16x16x32_bf16 v[112:115], v[174:177], v[186:189], v[112:115]
	v_mfma_f32_16x16x32_bf16 v[100:103], v[166:169], v[194:197], v[100:103]
	v_mfma_f32_16x16x32_bf16 v[96:99], v[174:177], v[194:197], v[96:99]
	v_mfma_f32_16x16x32_bf16 v[84:87], v[166:169], v[202:205], v[84:87]
	v_mfma_f32_16x16x32_bf16 v[80:83], v[174:177], v[202:205], v[80:83]
	v_mfma_f32_16x16x32_bf16 v[68:71], v[166:169], v[210:213], v[68:71]
	v_mfma_f32_16x16x32_bf16 v[64:67], v[174:177], v[210:213], v[64:67]
	s_setprio 0
	s_barrier
	s_add_i32 s30, s53, s36
	v_lshl_add_u64 v[182:183], v[182:183], 0, s[10:11]
	s_mov_b32 m0, s30
	ds_read_b128 v[178:181], v148 offset:49152
	ds_read_b128 v[186:189], v148 offset:50176
	ds_read_b128 v[190:193], v148 offset:51200
	ds_read_b128 v[194:197], v148 offset:52224
	ds_read_b128 v[198:201], v148 offset:53248
	ds_read_b128 v[202:205], v148 offset:54272
	ds_read_b128 v[206:209], v148 offset:55296
	ds_read_b128 v[210:213], v148 offset:56320
	global_load_lds_dwordx4 v[182:183], off
	s_add_i32 m0, s30, 0x2000
	s_add_u32 s28, s28, 0x40080
	v_lshl_add_u64 v[182:183], v[214:215], 0, s[10:11]
	s_addc_u32 s29, s29, 0
	s_add_i32 s30, s54, s36
	global_load_lds_dwordx4 v[182:183], off
	v_lshl_add_u64 v[182:183], s[28:29], 0, v[130:131]
	s_mov_b32 m0, s30
	s_nop 0
	global_load_lds_dwordx4 v[182:183], off
	v_lshl_add_u64 v[182:183], s[28:29], 0, v[134:135]
	s_add_i32 m0, s30, 0x2000
	s_nop 0
	global_load_lds_dwordx4 v[182:183], off
	v_lshl_add_u64 v[182:183], v[216:217], 0, s[10:11]
	s_mov_b32 m0, s44
	s_nop 0
	global_load_lds_dwordx4 v[182:183], off
	v_lshl_add_u64 v[182:183], v[218:219], 0, s[10:11]
	s_mov_b32 m0, s45
	s_nop 0
	global_load_lds_dwordx4 v[182:183], off
	s_waitcnt vmcnt(8)
	s_waitcnt lgkmcnt(0)
	s_barrier
	s_setprio 1
	s_waitcnt lgkmcnt(0)
	v_mfma_f32_16x16x32_bf16 v[60:63], v[140:143], v[178:181], v[60:63]
	v_mfma_f32_16x16x32_bf16 v[56:59], v[154:157], v[178:181], v[56:59]
	v_mfma_f32_16x16x32_bf16 v[44:47], v[140:143], v[190:193], v[44:47]
	v_mfma_f32_16x16x32_bf16 v[40:43], v[154:157], v[190:193], v[40:43]
	v_mfma_f32_16x16x32_bf16 v[28:31], v[140:143], v[198:201], v[28:31]
	v_mfma_f32_16x16x32_bf16 v[24:27], v[154:157], v[198:201], v[24:27]
	v_mfma_f32_16x16x32_bf16 v[12:15], v[140:143], v[206:209], v[12:15]
	v_mfma_f32_16x16x32_bf16 v[8:11], v[154:157], v[206:209], v[8:11]
	v_mfma_f32_16x16x32_bf16 v[60:63], v[150:153], v[186:189], v[60:63]
	v_mfma_f32_16x16x32_bf16 v[56:59], v[158:161], v[186:189], v[56:59]
	v_mfma_f32_16x16x32_bf16 v[44:47], v[150:153], v[194:197], v[44:47]
	v_mfma_f32_16x16x32_bf16 v[40:43], v[158:161], v[194:197], v[40:43]
	v_mfma_f32_16x16x32_bf16 v[28:31], v[150:153], v[202:205], v[28:31]
	v_mfma_f32_16x16x32_bf16 v[24:27], v[158:161], v[202:205], v[24:27]
	v_mfma_f32_16x16x32_bf16 v[12:15], v[150:153], v[210:213], v[12:15]
	v_mfma_f32_16x16x32_bf16 v[8:11], v[158:161], v[210:213], v[8:11]
	v_mfma_f32_16x16x32_bf16 v[52:55], v[162:165], v[178:181], v[52:55]
	v_mfma_f32_16x16x32_bf16 v[48:51], v[170:173], v[178:181], v[48:51]
	v_mfma_f32_16x16x32_bf16 v[36:39], v[162:165], v[190:193], v[36:39]
	v_mfma_f32_16x16x32_bf16 v[32:35], v[170:173], v[190:193], v[32:35]
	v_mfma_f32_16x16x32_bf16 v[20:23], v[162:165], v[198:201], v[20:23]
	v_mfma_f32_16x16x32_bf16 v[16:19], v[170:173], v[198:201], v[16:19]
	v_mfma_f32_16x16x32_bf16 v[4:7], v[162:165], v[206:209], v[4:7]
	v_mfma_f32_16x16x32_bf16 v[0:3], v[170:173], v[206:209], v[0:3]
	v_mfma_f32_16x16x32_bf16 v[52:55], v[166:169], v[186:189], v[52:55]
	v_mfma_f32_16x16x32_bf16 v[48:51], v[174:177], v[186:189], v[48:51]
	v_mfma_f32_16x16x32_bf16 v[36:39], v[166:169], v[194:197], v[36:39]
	v_mfma_f32_16x16x32_bf16 v[32:35], v[174:177], v[194:197], v[32:35]
	v_mfma_f32_16x16x32_bf16 v[20:23], v[166:169], v[202:205], v[20:23]
	v_mfma_f32_16x16x32_bf16 v[16:19], v[174:177], v[202:205], v[16:19]
	v_mfma_f32_16x16x32_bf16 v[4:7], v[166:169], v[210:213], v[4:7]
	v_mfma_f32_16x16x32_bf16 v[0:3], v[174:177], v[210:213], v[0:3]
	s_setprio 0
	s_barrier
	s_add_i32 s52, s52, 2
	s_add_u32 s26, s26, 0x100
	s_addc_u32 s27, s27, 0
	s_add_u32 s15, s15, 0x100
	s_addc_u32 s51, s51, 0
	s_cmp_gt_u32 s52, 13
	s_cbranch_scc0 .LBB0_792
	s_and_b64 vcc, exec, s[12:13]
	s_cbranch_vccz .LBB0_795
	s_barrier

.LBB0_883:
	ds_read_b128 v[140:143], v146
	ds_read_b128 v[150:153], v146 offset:1024
	ds_read_b128 v[154:157], v146 offset:2048
	ds_read_b128 v[158:161], v146 offset:3072
	ds_read_b128 v[162:165], v147
	ds_read_b128 v[166:169], v147 offset:1024
	ds_read_b128 v[170:173], v147 offset:2048
	ds_read_b128 v[174:177], v147 offset:3072
	s_add_u32 s28, s26, 0xfffc0080
	s_addc_u32 s29, s27, -1
	s_cmp_eq_u32 s49, 12
	s_cselect_b32 s31, s23, s29
	s_cselect_b32 s30, s22, s28
	s_cselect_b32 s29, s25, s48
	s_cselect_b32 s28, s24, s13
	v_lshl_add_u64 v[182:183], s[26:27], 0, v[136:137]
	s_add_i32 m0, s21, 0xc000
	ds_read_b128 v[178:181], v148
	ds_read_b128 v[186:189], v148 offset:1024
	ds_read_b128 v[190:193], v148 offset:2048
	ds_read_b128 v[194:197], v148 offset:3072
	ds_read_b128 v[198:201], v148 offset:4096
	ds_read_b128 v[202:205], v148 offset:5120
	ds_read_b128 v[206:209], v148 offset:6144
	ds_read_b128 v[210:213], v148 offset:7168
	global_load_lds_dwordx4 v[182:183], off
	v_lshl_add_u64 v[182:183], s[26:27], 0, v[138:139]
	s_add_i32 m0, s21, 0xe000
	s_nop 0
	global_load_lds_dwordx4 v[182:183], off
	s_waitcnt vmcnt(8)
	s_waitcnt lgkmcnt(0)
	s_barrier
	s_setprio 1
	s_waitcnt lgkmcnt(0)
	v_mfma_f32_16x16x32_bf16 v[124:127], v[140:143], v[178:181], v[124:127]
	v_mfma_f32_16x16x32_bf16 v[120:123], v[154:157], v[178:181], v[120:123]
	v_mfma_f32_16x16x32_bf16 v[108:111], v[140:143], v[190:193], v[108:111]
	v_mfma_f32_16x16x32_bf16 v[104:107], v[154:157], v[190:193], v[104:107]
	v_mfma_f32_16x16x32_bf16 v[92:95], v[140:143], v[198:201], v[92:95]
	v_mfma_f32_16x16x32_bf16 v[88:91], v[154:157], v[198:201], v[88:91]
	v_mfma_f32_16x16x32_bf16 v[76:79], v[140:143], v[206:209], v[76:79]
	v_mfma_f32_16x16x32_bf16 v[72:75], v[154:157], v[206:209], v[72:75]
	v_mfma_f32_16x16x32_bf16 v[124:127], v[150:153], v[186:189], v[124:127]
	v_mfma_f32_16x16x32_bf16 v[120:123], v[158:161], v[186:189], v[120:123]
	v_mfma_f32_16x16x32_bf16 v[108:111], v[150:153], v[194:197], v[108:111]
	v_mfma_f32_16x16x32_bf16 v[104:107], v[158:161], v[194:197], v[104:107]
	v_mfma_f32_16x16x32_bf16 v[92:95], v[150:153], v[202:205], v[92:95]
	v_mfma_f32_16x16x32_bf16 v[88:91], v[158:161], v[202:205], v[88:91]
	v_mfma_f32_16x16x32_bf16 v[76:79], v[150:153], v[210:213], v[76:79]
	v_mfma_f32_16x16x32_bf16 v[72:75], v[158:161], v[210:213], v[72:75]
	v_mfma_f32_16x16x32_bf16 v[116:119], v[162:165], v[178:181], v[116:119]
	v_mfma_f32_16x16x32_bf16 v[112:115], v[170:173], v[178:181], v[112:115]
	v_mfma_f32_16x16x32_bf16 v[100:103], v[162:165], v[190:193], v[100:103]
	v_mfma_f32_16x16x32_bf16 v[96:99], v[170:173], v[190:193], v[96:99]
	v_mfma_f32_16x16x32_bf16 v[84:87], v[162:165], v[198:201], v[84:87]
	v_mfma_f32_16x16x32_bf16 v[80:83], v[170:173], v[198:201], v[80:83]
	v_mfma_f32_16x16x32_bf16 v[68:71], v[162:165], v[206:209], v[68:71]
	v_mfma_f32_16x16x32_bf16 v[64:67], v[170:173], v[206:209], v[64:67]
	v_mfma_f32_16x16x32_bf16 v[116:119], v[166:169], v[186:189], v[116:119]
	v_mfma_f32_16x16x32_bf16 v[112:115], v[174:177], v[186:189], v[112:115]
	v_mfma_f32_16x16x32_bf16 v[100:103], v[166:169], v[194:197], v[100:103]
	v_mfma_f32_16x16x32_bf16 v[96:99], v[174:177], v[194:197], v[96:99]
	v_mfma_f32_16x16x32_bf16 v[84:87], v[166:169], v[202:205], v[84:87]
	v_mfma_f32_16x16x32_bf16 v[80:83], v[174:177], v[202:205], v[80:83]
	v_mfma_f32_16x16x32_bf16 v[68:71], v[166:169], v[210:213], v[68:71]
	v_mfma_f32_16x16x32_bf16 v[64:67], v[174:177], v[210:213], v[64:67]
	s_setprio 0
	s_barrier
	s_add_i32 s51, s44, s35
	v_lshl_add_u64 v[182:183], s[28:29], 0, v[132:133]
	s_mov_b32 m0, s51
	ds_read_b128 v[178:181], v148 offset:16384
	ds_read_b128 v[186:189], v148 offset:17408
	ds_read_b128 v[190:193], v148 offset:18432
	ds_read_b128 v[194:197], v148 offset:19456
	ds_read_b128 v[198:201], v148 offset:20480
	ds_read_b128 v[202:205], v148 offset:21504
	ds_read_b128 v[206:209], v148 offset:22528
	ds_read_b128 v[210:213], v148 offset:23552
	global_load_lds_dwordx4 v[182:183], off
	s_add_i32 m0, s51, 0x2000
	s_add_u32 s52, s28, 0x40000
	v_lshl_add_u64 v[214:215], s[28:29], 0, v[128:129]
	s_addc_u32 s53, s29, 0
	s_add_i32 s51, s45, s35
	global_load_lds_dwordx4 v[214:215], off
	v_lshl_add_u64 v[216:217], s[52:53], 0, v[132:133]
	s_mov_b32 m0, s51
	v_lshl_add_u64 v[218:219], s[30:31], 0, v[130:131]
	global_load_lds_dwordx4 v[216:217], off
	v_lshl_add_u64 v[216:217], s[52:53], 0, v[128:129]
	s_add_i32 m0, s51, 0x2000
	s_nop 0
	global_load_lds_dwordx4 v[216:217], off
	v_lshl_add_u64 v[216:217], s[30:31], 0, v[134:135]
	s_mov_b32 m0, s21
	s_nop 0
	global_load_lds_dwordx4 v[216:217], off
	s_mov_b32 m0, s36
	s_nop 0
	global_load_lds_dwordx4 v[218:219], off
	s_waitcnt vmcnt(8)
	s_waitcnt lgkmcnt(0)
	s_barrier
	s_setprio 1
	s_waitcnt lgkmcnt(0)
	v_mfma_f32_16x16x32_bf16 v[60:63], v[140:143], v[178:181], v[60:63]
	v_mfma_f32_16x16x32_bf16 v[56:59], v[154:157], v[178:181], v[56:59]
	v_mfma_f32_16x16x32_bf16 v[44:47], v[140:143], v[190:193], v[44:47]
	v_mfma_f32_16x16x32_bf16 v[40:43], v[154:157], v[190:193], v[40:43]
	v_mfma_f32_16x16x32_bf16 v[28:31], v[140:143], v[198:201], v[28:31]
	v_mfma_f32_16x16x32_bf16 v[24:27], v[154:157], v[198:201], v[24:27]
	v_mfma_f32_16x16x32_bf16 v[12:15], v[140:143], v[206:209], v[12:15]
	v_mfma_f32_16x16x32_bf16 v[8:11], v[154:157], v[206:209], v[8:11]
	v_mfma_f32_16x16x32_bf16 v[60:63], v[150:153], v[186:189], v[60:63]
	v_mfma_f32_16x16x32_bf16 v[56:59], v[158:161], v[186:189], v[56:59]
	v_mfma_f32_16x16x32_bf16 v[44:47], v[150:153], v[194:197], v[44:47]
	v_mfma_f32_16x16x32_bf16 v[40:43], v[158:161], v[194:197], v[40:43]
	v_mfma_f32_16x16x32_bf16 v[28:31], v[150:153], v[202:205], v[28:31]
	v_mfma_f32_16x16x32_bf16 v[24:27], v[158:161], v[202:205], v[24:27]
	v_mfma_f32_16x16x32_bf16 v[12:15], v[150:153], v[210:213], v[12:15]
	v_mfma_f32_16x16x32_bf16 v[8:11], v[158:161], v[210:213], v[8:11]
	v_mfma_f32_16x16x32_bf16 v[52:55], v[162:165], v[178:181], v[52:55]
	v_mfma_f32_16x16x32_bf16 v[48:51], v[170:173], v[178:181], v[48:51]
	v_mfma_f32_16x16x32_bf16 v[36:39], v[162:165], v[190:193], v[36:39]
	v_mfma_f32_16x16x32_bf16 v[32:35], v[170:173], v[190:193], v[32:35]
	v_mfma_f32_16x16x32_bf16 v[20:23], v[162:165], v[198:201], v[20:23]
	v_mfma_f32_16x16x32_bf16 v[16:19], v[170:173], v[198:201], v[16:19]
	v_mfma_f32_16x16x32_bf16 v[4:7], v[162:165], v[206:209], v[4:7]
	v_mfma_f32_16x16x32_bf16 v[0:3], v[170:173], v[206:209], v[0:3]
	v_mfma_f32_16x16x32_bf16 v[52:55], v[166:169], v[186:189], v[52:55]
	v_mfma_f32_16x16x32_bf16 v[48:51], v[174:177], v[186:189], v[48:51]
	v_mfma_f32_16x16x32_bf16 v[36:39], v[166:169], v[194:197], v[36:39]
	v_mfma_f32_16x16x32_bf16 v[32:35], v[174:177], v[194:197], v[32:35]
	v_mfma_f32_16x16x32_bf16 v[20:23], v[166:169], v[202:205], v[20:23]
	v_mfma_f32_16x16x32_bf16 v[16:19], v[174:177], v[202:205], v[16:19]
	v_mfma_f32_16x16x32_bf16 v[4:7], v[166:169], v[210:213], v[4:7]
	v_mfma_f32_16x16x32_bf16 v[0:3], v[174:177], v[210:213], v[0:3]
	s_setprio 0
	s_barrier
	s_add_i32 s51, 0, 0x18000
	s_add_i32 s52, 0, 0x1c000
	v_add_u32_e32 v158, s51, v145
	v_add_u32_e32 v174, s52, v145
	ds_read_b128 v[140:143], v158
	ds_read_b128 v[150:153], v158 offset:1024
	ds_read_b128 v[154:157], v158 offset:2048
	ds_read_b128 v[158:161], v158 offset:3072
	ds_read_b128 v[162:165], v174
	ds_read_b128 v[166:169], v174 offset:1024
	ds_read_b128 v[170:173], v174 offset:2048
	ds_read_b128 v[174:177], v174 offset:3072
	s_add_u32 s30, s30, 0x40000
	s_addc_u32 s31, s31, 0
	s_mov_b32 m0, s37
	v_lshl_add_u64 v[220:221], s[30:31], 0, v[134:135]
	ds_read_b128 v[178:181], v148 offset:32768
	ds_read_b128 v[186:189], v148 offset:33792
	ds_read_b128 v[190:193], v148 offset:34816
	ds_read_b128 v[194:197], v148 offset:35840
	ds_read_b128 v[198:201], v148 offset:36864
	ds_read_b128 v[202:205], v148 offset:37888
	ds_read_b128 v[206:209], v148 offset:38912
	ds_read_b128 v[210:213], v148 offset:39936
	global_load_lds_dwordx4 v[220:221], off
	v_lshl_add_u64 v[220:221], s[30:31], 0, v[130:131]
	s_mov_b32 m0, s38
	s_nop 0
	global_load_lds_dwordx4 v[220:221], off
	s_waitcnt vmcnt(8)
	s_waitcnt lgkmcnt(0)
	s_barrier
	s_setprio 1
	s_waitcnt lgkmcnt(0)
	v_mfma_f32_16x16x32_bf16 v[124:127], v[140:143], v[178:181], v[124:127]
	v_mfma_f32_16x16x32_bf16 v[120:123], v[154:157], v[178:181], v[120:123]
	v_mfma_f32_16x16x32_bf16 v[108:111], v[140:143], v[190:193], v[108:111]
	v_mfma_f32_16x16x32_bf16 v[104:107], v[154:157], v[190:193], v[104:107]
	v_mfma_f32_16x16x32_bf16 v[92:95], v[140:143], v[198:201], v[92:95]
	v_mfma_f32_16x16x32_bf16 v[88:91], v[154:157], v[198:201], v[88:91]
	v_mfma_f32_16x16x32_bf16 v[76:79], v[140:143], v[206:209], v[76:79]
	v_mfma_f32_16x16x32_bf16 v[72:75], v[154:157], v[206:209], v[72:75]
	v_mfma_f32_16x16x32_bf16 v[124:127], v[150:153], v[186:189], v[124:127]
	v_mfma_f32_16x16x32_bf16 v[120:123], v[158:161], v[186:189], v[120:123]
	v_mfma_f32_16x16x32_bf16 v[108:111], v[150:153], v[194:197], v[108:111]
	v_mfma_f32_16x16x32_bf16 v[104:107], v[158:161], v[194:197], v[104:107]
	v_mfma_f32_16x16x32_bf16 v[92:95], v[150:153], v[202:205], v[92:95]
	v_mfma_f32_16x16x32_bf16 v[88:91], v[158:161], v[202:205], v[88:91]
	v_mfma_f32_16x16x32_bf16 v[76:79], v[150:153], v[210:213], v[76:79]
	v_mfma_f32_16x16x32_bf16 v[72:75], v[158:161], v[210:213], v[72:75]
	v_mfma_f32_16x16x32_bf16 v[116:119], v[162:165], v[178:181], v[116:119]
	v_mfma_f32_16x16x32_bf16 v[112:115], v[170:173], v[178:181], v[112:115]
	v_mfma_f32_16x16x32_bf16 v[100:103], v[162:165], v[190:193], v[100:103]
	v_mfma_f32_16x16x32_bf16 v[96:99], v[170:173], v[190:193], v[96:99]
	v_mfma_f32_16x16x32_bf16 v[84:87], v[162:165], v[198:201], v[84:87]
	v_mfma_f32_16x16x32_bf16 v[80:83], v[170:173], v[198:201], v[80:83]
	v_mfma_f32_16x16x32_bf16 v[68:71], v[162:165], v[206:209], v[68:71]
	v_mfma_f32_16x16x32_bf16 v[64:67], v[170:173], v[206:209], v[64:67]
	v_mfma_f32_16x16x32_bf16 v[116:119], v[166:169], v[186:189], v[116:119]
	v_mfma_f32_16x16x32_bf16 v[112:115], v[174:177], v[186:189], v[112:115]
	v_mfma_f32_16x16x32_bf16 v[100:103], v[166:169], v[194:197], v[100:103]
	v_mfma_f32_16x16x32_bf16 v[96:99], v[174:177], v[194:197], v[96:99]
	v_mfma_f32_16x16x32_bf16 v[84:87], v[166:169], v[202:205], v[84:87]
	v_mfma_f32_16x16x32_bf16 v[80:83], v[174:177], v[202:205], v[80:83]
	v_mfma_f32_16x16x32_bf16 v[68:71], v[166:169], v[210:213], v[68:71]
	v_mfma_f32_16x16x32_bf16 v[64:67], v[174:177], v[210:213], v[64:67]
	s_setprio 0
	s_barrier
	s_add_i32 s30, s51, s35
	v_lshl_add_u64 v[182:183], v[182:183], 0, s[8:9]
	s_mov_b32 m0, s30
	ds_read_b128 v[178:181], v148 offset:49152
	ds_read_b128 v[186:189], v148 offset:50176
	ds_read_b128 v[190:193], v148 offset:51200
	ds_read_b128 v[194:197], v148 offset:52224
	ds_read_b128 v[198:201], v148 offset:53248
	ds_read_b128 v[202:205], v148 offset:54272
	ds_read_b128 v[206:209], v148 offset:55296
	ds_read_b128 v[210:213], v148 offset:56320
	global_load_lds_dwordx4 v[182:183], off
	s_add_i32 m0, s30, 0x2000
	s_add_u32 s28, s28, 0x40080
	v_lshl_add_u64 v[182:183], v[214:215], 0, s[8:9]
	s_addc_u32 s29, s29, 0
	s_add_i32 s30, s52, s35
	global_load_lds_dwordx4 v[182:183], off
	v_lshl_add_u64 v[182:183], s[28:29], 0, v[132:133]
	s_mov_b32 m0, s30
	s_nop 0
	global_load_lds_dwordx4 v[182:183], off
	v_lshl_add_u64 v[182:183], s[28:29], 0, v[128:129]
	s_add_i32 m0, s30, 0x2000
	s_nop 0
	global_load_lds_dwordx4 v[182:183], off
	v_lshl_add_u64 v[182:183], v[216:217], 0, s[8:9]
	s_mov_b32 m0, s42
	s_nop 0
	global_load_lds_dwordx4 v[182:183], off
	v_lshl_add_u64 v[182:183], v[218:219], 0, s[8:9]
	s_mov_b32 m0, s43
	s_nop 0
	global_load_lds_dwordx4 v[182:183], off
	s_waitcnt vmcnt(8)
	s_waitcnt lgkmcnt(0)
	s_barrier
	s_setprio 1
	s_waitcnt lgkmcnt(0)
	v_mfma_f32_16x16x32_bf16 v[60:63], v[140:143], v[178:181], v[60:63]
	v_mfma_f32_16x16x32_bf16 v[56:59], v[154:157], v[178:181], v[56:59]
	v_mfma_f32_16x16x32_bf16 v[44:47], v[140:143], v[190:193], v[44:47]
	v_mfma_f32_16x16x32_bf16 v[40:43], v[154:157], v[190:193], v[40:43]
	v_mfma_f32_16x16x32_bf16 v[28:31], v[140:143], v[198:201], v[28:31]
	v_mfma_f32_16x16x32_bf16 v[24:27], v[154:157], v[198:201], v[24:27]
	v_mfma_f32_16x16x32_bf16 v[12:15], v[140:143], v[206:209], v[12:15]
	v_mfma_f32_16x16x32_bf16 v[8:11], v[154:157], v[206:209], v[8:11]
	v_mfma_f32_16x16x32_bf16 v[60:63], v[150:153], v[186:189], v[60:63]
	v_mfma_f32_16x16x32_bf16 v[56:59], v[158:161], v[186:189], v[56:59]
	v_mfma_f32_16x16x32_bf16 v[44:47], v[150:153], v[194:197], v[44:47]
	v_mfma_f32_16x16x32_bf16 v[40:43], v[158:161], v[194:197], v[40:43]
	v_mfma_f32_16x16x32_bf16 v[28:31], v[150:153], v[202:205], v[28:31]
	v_mfma_f32_16x16x32_bf16 v[24:27], v[158:161], v[202:205], v[24:27]
	v_mfma_f32_16x16x32_bf16 v[12:15], v[150:153], v[210:213], v[12:15]
	v_mfma_f32_16x16x32_bf16 v[8:11], v[158:161], v[210:213], v[8:11]
	v_mfma_f32_16x16x32_bf16 v[52:55], v[162:165], v[178:181], v[52:55]
	v_mfma_f32_16x16x32_bf16 v[48:51], v[170:173], v[178:181], v[48:51]
	v_mfma_f32_16x16x32_bf16 v[36:39], v[162:165], v[190:193], v[36:39]
	v_mfma_f32_16x16x32_bf16 v[32:35], v[170:173], v[190:193], v[32:35]
	v_mfma_f32_16x16x32_bf16 v[20:23], v[162:165], v[198:201], v[20:23]
	v_mfma_f32_16x16x32_bf16 v[16:19], v[170:173], v[198:201], v[16:19]
	v_mfma_f32_16x16x32_bf16 v[4:7], v[162:165], v[206:209], v[4:7]
	v_mfma_f32_16x16x32_bf16 v[0:3], v[170:173], v[206:209], v[0:3]
	v_mfma_f32_16x16x32_bf16 v[52:55], v[166:169], v[186:189], v[52:55]
	v_mfma_f32_16x16x32_bf16 v[48:51], v[174:177], v[186:189], v[48:51]
	v_mfma_f32_16x16x32_bf16 v[36:39], v[166:169], v[194:197], v[36:39]
	v_mfma_f32_16x16x32_bf16 v[32:35], v[174:177], v[194:197], v[32:35]
	v_mfma_f32_16x16x32_bf16 v[20:23], v[166:169], v[202:205], v[20:23]
	v_mfma_f32_16x16x32_bf16 v[16:19], v[174:177], v[202:205], v[16:19]
	v_mfma_f32_16x16x32_bf16 v[4:7], v[166:169], v[210:213], v[4:7]
	v_mfma_f32_16x16x32_bf16 v[0:3], v[174:177], v[210:213], v[0:3]
	s_setprio 0
	s_barrier
	s_add_i32 s49, s49, 2
	s_add_u32 s26, s26, 0x100
	s_addc_u32 s27, s27, 0
	s_add_u32 s13, s13, 0x100
	s_addc_u32 s48, s48, 0
	s_cmp_gt_u32 s49, 13
	s_cbranch_scc0 .LBB0_883
	s_and_b64 vcc, exec, s[10:11]
	s_cbranch_vccz .LBB0_886
	s_barrier

.LBB0_960:
	ds_read_b128 v[140:143], v146
	ds_read_b128 v[150:153], v146 offset:1024
	ds_read_b128 v[154:157], v146 offset:2048
	ds_read_b128 v[158:161], v146 offset:3072
	ds_read_b128 v[162:165], v147
	ds_read_b128 v[166:169], v147 offset:1024
	ds_read_b128 v[170:173], v147 offset:2048
	ds_read_b128 v[174:177], v147 offset:3072
	s_add_u32 s28, s26, 0xfff00080
	s_addc_u32 s29, s27, -1
	s_cmp_eq_u32 s52, 60
	s_cselect_b32 s31, s23, s29
	s_cselect_b32 s30, s22, s28
	s_cselect_b32 s29, s25, s51
	s_cselect_b32 s28, s24, s15
	v_lshl_add_u64 v[182:183], s[26:27], 0, v[136:137]
	s_add_i32 m0, s37, 0xc000
	ds_read_b128 v[178:181], v148
	ds_read_b128 v[186:189], v148 offset:1024
	ds_read_b128 v[190:193], v148 offset:2048
	ds_read_b128 v[194:197], v148 offset:3072
	ds_read_b128 v[198:201], v148 offset:4096
	ds_read_b128 v[202:205], v148 offset:5120
	ds_read_b128 v[206:209], v148 offset:6144
	ds_read_b128 v[210:213], v148 offset:7168
	global_load_lds_dwordx4 v[182:183], off
	v_lshl_add_u64 v[182:183], s[26:27], 0, v[138:139]
	s_add_i32 m0, s37, 0xe000
	s_nop 0
	global_load_lds_dwordx4 v[182:183], off
	s_waitcnt vmcnt(8)
	s_waitcnt lgkmcnt(0)
	s_barrier
	s_setprio 1
	s_waitcnt lgkmcnt(0)
	v_mfma_f32_16x16x32_bf16 v[124:127], v[140:143], v[178:181], v[124:127]
	v_mfma_f32_16x16x32_bf16 v[120:123], v[154:157], v[178:181], v[120:123]
	v_mfma_f32_16x16x32_bf16 v[108:111], v[140:143], v[190:193], v[108:111]
	v_mfma_f32_16x16x32_bf16 v[104:107], v[154:157], v[190:193], v[104:107]
	v_mfma_f32_16x16x32_bf16 v[92:95], v[140:143], v[198:201], v[92:95]
	v_mfma_f32_16x16x32_bf16 v[88:91], v[154:157], v[198:201], v[88:91]
	v_mfma_f32_16x16x32_bf16 v[76:79], v[140:143], v[206:209], v[76:79]
	v_mfma_f32_16x16x32_bf16 v[72:75], v[154:157], v[206:209], v[72:75]
	v_mfma_f32_16x16x32_bf16 v[124:127], v[150:153], v[186:189], v[124:127]
	v_mfma_f32_16x16x32_bf16 v[120:123], v[158:161], v[186:189], v[120:123]
	v_mfma_f32_16x16x32_bf16 v[108:111], v[150:153], v[194:197], v[108:111]
	v_mfma_f32_16x16x32_bf16 v[104:107], v[158:161], v[194:197], v[104:107]
	v_mfma_f32_16x16x32_bf16 v[92:95], v[150:153], v[202:205], v[92:95]
	v_mfma_f32_16x16x32_bf16 v[88:91], v[158:161], v[202:205], v[88:91]
	v_mfma_f32_16x16x32_bf16 v[76:79], v[150:153], v[210:213], v[76:79]
	v_mfma_f32_16x16x32_bf16 v[72:75], v[158:161], v[210:213], v[72:75]
	v_mfma_f32_16x16x32_bf16 v[116:119], v[162:165], v[178:181], v[116:119]
	v_mfma_f32_16x16x32_bf16 v[112:115], v[170:173], v[178:181], v[112:115]
	v_mfma_f32_16x16x32_bf16 v[100:103], v[162:165], v[190:193], v[100:103]
	v_mfma_f32_16x16x32_bf16 v[96:99], v[170:173], v[190:193], v[96:99]
	v_mfma_f32_16x16x32_bf16 v[84:87], v[162:165], v[198:201], v[84:87]
	v_mfma_f32_16x16x32_bf16 v[80:83], v[170:173], v[198:201], v[80:83]
	v_mfma_f32_16x16x32_bf16 v[68:71], v[162:165], v[206:209], v[68:71]
	v_mfma_f32_16x16x32_bf16 v[64:67], v[170:173], v[206:209], v[64:67]
	v_mfma_f32_16x16x32_bf16 v[116:119], v[166:169], v[186:189], v[116:119]
	v_mfma_f32_16x16x32_bf16 v[112:115], v[174:177], v[186:189], v[112:115]
	v_mfma_f32_16x16x32_bf16 v[100:103], v[166:169], v[194:197], v[100:103]
	v_mfma_f32_16x16x32_bf16 v[96:99], v[174:177], v[194:197], v[96:99]
	v_mfma_f32_16x16x32_bf16 v[84:87], v[166:169], v[202:205], v[84:87]
	v_mfma_f32_16x16x32_bf16 v[80:83], v[174:177], v[202:205], v[80:83]
	v_mfma_f32_16x16x32_bf16 v[68:71], v[166:169], v[210:213], v[68:71]
	v_mfma_f32_16x16x32_bf16 v[64:67], v[174:177], v[210:213], v[64:67]
	s_setprio 0
	s_barrier
	s_add_i32 s53, s46, s36
	v_lshl_add_u64 v[182:183], s[28:29], 0, v[130:131]
	s_mov_b32 m0, s53
	ds_read_b128 v[178:181], v148 offset:16384
	ds_read_b128 v[186:189], v148 offset:17408
	ds_read_b128 v[190:193], v148 offset:18432
	ds_read_b128 v[194:197], v148 offset:19456
	ds_read_b128 v[198:201], v148 offset:20480
	ds_read_b128 v[202:205], v148 offset:21504
	ds_read_b128 v[206:209], v148 offset:22528
	ds_read_b128 v[210:213], v148 offset:23552
	global_load_lds_dwordx4 v[182:183], off
	s_add_i32 m0, s53, 0x2000
	s_add_u32 s54, s28, 0x100000
	v_lshl_add_u64 v[214:215], s[28:29], 0, v[134:135]
	s_addc_u32 s55, s29, 0
	s_add_i32 s53, s47, s36
	global_load_lds_dwordx4 v[214:215], off
	v_lshl_add_u64 v[216:217], s[54:55], 0, v[130:131]
	s_mov_b32 m0, s53
	v_lshl_add_u64 v[218:219], s[30:31], 0, v[132:133]
	global_load_lds_dwordx4 v[216:217], off
	v_lshl_add_u64 v[216:217], s[54:55], 0, v[134:135]
	s_add_i32 m0, s53, 0x2000
	s_nop 0
	global_load_lds_dwordx4 v[216:217], off
	v_lshl_add_u64 v[216:217], s[30:31], 0, v[128:129]
	s_mov_b32 m0, s37
	s_nop 0
	global_load_lds_dwordx4 v[216:217], off
	s_mov_b32 m0, s38
	s_nop 0
	global_load_lds_dwordx4 v[218:219], off
	s_waitcnt vmcnt(8)
	s_waitcnt lgkmcnt(0)
	s_barrier
	s_setprio 1
	s_waitcnt lgkmcnt(0)
	v_mfma_f32_16x16x32_bf16 v[60:63], v[140:143], v[178:181], v[60:63]
	v_mfma_f32_16x16x32_bf16 v[56:59], v[154:157], v[178:181], v[56:59]
	v_mfma_f32_16x16x32_bf16 v[44:47], v[140:143], v[190:193], v[44:47]
	v_mfma_f32_16x16x32_bf16 v[40:43], v[154:157], v[190:193], v[40:43]
	v_mfma_f32_16x16x32_bf16 v[28:31], v[140:143], v[198:201], v[28:31]
	v_mfma_f32_16x16x32_bf16 v[24:27], v[154:157], v[198:201], v[24:27]
	v_mfma_f32_16x16x32_bf16 v[12:15], v[140:143], v[206:209], v[12:15]
	v_mfma_f32_16x16x32_bf16 v[8:11], v[154:157], v[206:209], v[8:11]
	v_mfma_f32_16x16x32_bf16 v[60:63], v[150:153], v[186:189], v[60:63]
	v_mfma_f32_16x16x32_bf16 v[56:59], v[158:161], v[186:189], v[56:59]
	v_mfma_f32_16x16x32_bf16 v[44:47], v[150:153], v[194:197], v[44:47]
	v_mfma_f32_16x16x32_bf16 v[40:43], v[158:161], v[194:197], v[40:43]
	v_mfma_f32_16x16x32_bf16 v[28:31], v[150:153], v[202:205], v[28:31]
	v_mfma_f32_16x16x32_bf16 v[24:27], v[158:161], v[202:205], v[24:27]
	v_mfma_f32_16x16x32_bf16 v[12:15], v[150:153], v[210:213], v[12:15]
	v_mfma_f32_16x16x32_bf16 v[8:11], v[158:161], v[210:213], v[8:11]
	v_mfma_f32_16x16x32_bf16 v[52:55], v[162:165], v[178:181], v[52:55]
	v_mfma_f32_16x16x32_bf16 v[48:51], v[170:173], v[178:181], v[48:51]
	v_mfma_f32_16x16x32_bf16 v[36:39], v[162:165], v[190:193], v[36:39]
	v_mfma_f32_16x16x32_bf16 v[32:35], v[170:173], v[190:193], v[32:35]
	v_mfma_f32_16x16x32_bf16 v[20:23], v[162:165], v[198:201], v[20:23]
	v_mfma_f32_16x16x32_bf16 v[16:19], v[170:173], v[198:201], v[16:19]
	v_mfma_f32_16x16x32_bf16 v[4:7], v[162:165], v[206:209], v[4:7]
	v_mfma_f32_16x16x32_bf16 v[0:3], v[170:173], v[206:209], v[0:3]
	v_mfma_f32_16x16x32_bf16 v[52:55], v[166:169], v[186:189], v[52:55]
	v_mfma_f32_16x16x32_bf16 v[48:51], v[174:177], v[186:189], v[48:51]
	v_mfma_f32_16x16x32_bf16 v[36:39], v[166:169], v[194:197], v[36:39]
	v_mfma_f32_16x16x32_bf16 v[32:35], v[174:177], v[194:197], v[32:35]
	v_mfma_f32_16x16x32_bf16 v[20:23], v[166:169], v[202:205], v[20:23]
	v_mfma_f32_16x16x32_bf16 v[16:19], v[174:177], v[202:205], v[16:19]
	v_mfma_f32_16x16x32_bf16 v[4:7], v[166:169], v[210:213], v[4:7]
	v_mfma_f32_16x16x32_bf16 v[0:3], v[174:177], v[210:213], v[0:3]
	s_setprio 0
	s_barrier
	s_add_i32 s53, 0, 0x18000
	s_add_i32 s54, 0, 0x1c000
	v_add_u32_e32 v158, s53, v145
	v_add_u32_e32 v174, s54, v145
	ds_read_b128 v[140:143], v158
	ds_read_b128 v[150:153], v158 offset:1024
	ds_read_b128 v[154:157], v158 offset:2048
	ds_read_b128 v[158:161], v158 offset:3072
	ds_read_b128 v[162:165], v174
	ds_read_b128 v[166:169], v174 offset:1024
	ds_read_b128 v[170:173], v174 offset:2048
	ds_read_b128 v[174:177], v174 offset:3072
	s_add_u32 s30, s30, 0x100000
	s_addc_u32 s31, s31, 0
	s_mov_b32 m0, s39
	v_lshl_add_u64 v[220:221], s[30:31], 0, v[128:129]
	ds_read_b128 v[178:181], v148 offset:32768
	ds_read_b128 v[186:189], v148 offset:33792
	ds_read_b128 v[190:193], v148 offset:34816
	ds_read_b128 v[194:197], v148 offset:35840
	ds_read_b128 v[198:201], v148 offset:36864
	ds_read_b128 v[202:205], v148 offset:37888
	ds_read_b128 v[206:209], v148 offset:38912
	ds_read_b128 v[210:213], v148 offset:39936
	global_load_lds_dwordx4 v[220:221], off
	v_lshl_add_u64 v[220:221], s[30:31], 0, v[132:133]
	s_mov_b32 m0, s40
	s_nop 0
	global_load_lds_dwordx4 v[220:221], off
	s_waitcnt vmcnt(8)
	s_waitcnt lgkmcnt(0)
	s_barrier
	s_setprio 1
	s_waitcnt lgkmcnt(0)
	v_mfma_f32_16x16x32_bf16 v[124:127], v[140:143], v[178:181], v[124:127]
	v_mfma_f32_16x16x32_bf16 v[120:123], v[154:157], v[178:181], v[120:123]
	v_mfma_f32_16x16x32_bf16 v[108:111], v[140:143], v[190:193], v[108:111]
	v_mfma_f32_16x16x32_bf16 v[104:107], v[154:157], v[190:193], v[104:107]
	v_mfma_f32_16x16x32_bf16 v[92:95], v[140:143], v[198:201], v[92:95]
	v_mfma_f32_16x16x32_bf16 v[88:91], v[154:157], v[198:201], v[88:91]
	v_mfma_f32_16x16x32_bf16 v[76:79], v[140:143], v[206:209], v[76:79]
	v_mfma_f32_16x16x32_bf16 v[72:75], v[154:157], v[206:209], v[72:75]
	v_mfma_f32_16x16x32_bf16 v[124:127], v[150:153], v[186:189], v[124:127]
	v_mfma_f32_16x16x32_bf16 v[120:123], v[158:161], v[186:189], v[120:123]
	v_mfma_f32_16x16x32_bf16 v[108:111], v[150:153], v[194:197], v[108:111]
	v_mfma_f32_16x16x32_bf16 v[104:107], v[158:161], v[194:197], v[104:107]
	v_mfma_f32_16x16x32_bf16 v[92:95], v[150:153], v[202:205], v[92:95]
	v_mfma_f32_16x16x32_bf16 v[88:91], v[158:161], v[202:205], v[88:91]
	v_mfma_f32_16x16x32_bf16 v[76:79], v[150:153], v[210:213], v[76:79]
	v_mfma_f32_16x16x32_bf16 v[72:75], v[158:161], v[210:213], v[72:75]
	v_mfma_f32_16x16x32_bf16 v[116:119], v[162:165], v[178:181], v[116:119]
	v_mfma_f32_16x16x32_bf16 v[112:115], v[170:173], v[178:181], v[112:115]
	v_mfma_f32_16x16x32_bf16 v[100:103], v[162:165], v[190:193], v[100:103]
	v_mfma_f32_16x16x32_bf16 v[96:99], v[170:173], v[190:193], v[96:99]
	v_mfma_f32_16x16x32_bf16 v[84:87], v[162:165], v[198:201], v[84:87]
	v_mfma_f32_16x16x32_bf16 v[80:83], v[170:173], v[198:201], v[80:83]
	v_mfma_f32_16x16x32_bf16 v[68:71], v[162:165], v[206:209], v[68:71]
	v_mfma_f32_16x16x32_bf16 v[64:67], v[170:173], v[206:209], v[64:67]
	v_mfma_f32_16x16x32_bf16 v[116:119], v[166:169], v[186:189], v[116:119]
	v_mfma_f32_16x16x32_bf16 v[112:115], v[174:177], v[186:189], v[112:115]
	v_mfma_f32_16x16x32_bf16 v[100:103], v[166:169], v[194:197], v[100:103]
	v_mfma_f32_16x16x32_bf16 v[96:99], v[174:177], v[194:197], v[96:99]
	v_mfma_f32_16x16x32_bf16 v[84:87], v[166:169], v[202:205], v[84:87]
	v_mfma_f32_16x16x32_bf16 v[80:83], v[174:177], v[202:205], v[80:83]
	v_mfma_f32_16x16x32_bf16 v[68:71], v[166:169], v[210:213], v[68:71]
	v_mfma_f32_16x16x32_bf16 v[64:67], v[174:177], v[210:213], v[64:67]
	s_setprio 0
	s_barrier
	s_add_i32 s30, s53, s36
	v_lshl_add_u64 v[182:183], v[182:183], 0, s[10:11]
	s_mov_b32 m0, s30
	ds_read_b128 v[178:181], v148 offset:49152
	ds_read_b128 v[186:189], v148 offset:50176
	ds_read_b128 v[190:193], v148 offset:51200
	ds_read_b128 v[194:197], v148 offset:52224
	ds_read_b128 v[198:201], v148 offset:53248
	ds_read_b128 v[202:205], v148 offset:54272
	ds_read_b128 v[206:209], v148 offset:55296
	ds_read_b128 v[210:213], v148 offset:56320
	global_load_lds_dwordx4 v[182:183], off
	s_add_i32 m0, s30, 0x2000
	s_add_u32 s28, s28, 0x100080
	v_lshl_add_u64 v[182:183], v[214:215], 0, s[10:11]
	s_addc_u32 s29, s29, 0
	s_add_i32 s30, s54, s36
	global_load_lds_dwordx4 v[182:183], off
	v_lshl_add_u64 v[182:183], s[28:29], 0, v[130:131]
	s_mov_b32 m0, s30
	s_nop 0
	global_load_lds_dwordx4 v[182:183], off
	v_lshl_add_u64 v[182:183], s[28:29], 0, v[134:135]
	s_add_i32 m0, s30, 0x2000
	s_nop 0
	global_load_lds_dwordx4 v[182:183], off
	v_lshl_add_u64 v[182:183], v[216:217], 0, s[10:11]
	s_mov_b32 m0, s44
	s_nop 0
	global_load_lds_dwordx4 v[182:183], off
	v_lshl_add_u64 v[182:183], v[218:219], 0, s[10:11]
	s_mov_b32 m0, s45
	s_nop 0
	global_load_lds_dwordx4 v[182:183], off
	s_waitcnt vmcnt(8)
	s_waitcnt lgkmcnt(0)
	s_barrier
	s_setprio 1
	s_waitcnt lgkmcnt(0)
	v_mfma_f32_16x16x32_bf16 v[60:63], v[140:143], v[178:181], v[60:63]
	v_mfma_f32_16x16x32_bf16 v[56:59], v[154:157], v[178:181], v[56:59]
	v_mfma_f32_16x16x32_bf16 v[44:47], v[140:143], v[190:193], v[44:47]
	v_mfma_f32_16x16x32_bf16 v[40:43], v[154:157], v[190:193], v[40:43]
	v_mfma_f32_16x16x32_bf16 v[28:31], v[140:143], v[198:201], v[28:31]
	v_mfma_f32_16x16x32_bf16 v[24:27], v[154:157], v[198:201], v[24:27]
	v_mfma_f32_16x16x32_bf16 v[12:15], v[140:143], v[206:209], v[12:15]
	v_mfma_f32_16x16x32_bf16 v[8:11], v[154:157], v[206:209], v[8:11]
	v_mfma_f32_16x16x32_bf16 v[60:63], v[150:153], v[186:189], v[60:63]
	v_mfma_f32_16x16x32_bf16 v[56:59], v[158:161], v[186:189], v[56:59]
	v_mfma_f32_16x16x32_bf16 v[44:47], v[150:153], v[194:197], v[44:47]
	v_mfma_f32_16x16x32_bf16 v[40:43], v[158:161], v[194:197], v[40:43]
	v_mfma_f32_16x16x32_bf16 v[28:31], v[150:153], v[202:205], v[28:31]
	v_mfma_f32_16x16x32_bf16 v[24:27], v[158:161], v[202:205], v[24:27]
	v_mfma_f32_16x16x32_bf16 v[12:15], v[150:153], v[210:213], v[12:15]
	v_mfma_f32_16x16x32_bf16 v[8:11], v[158:161], v[210:213], v[8:11]
	v_mfma_f32_16x16x32_bf16 v[52:55], v[162:165], v[178:181], v[52:55]
	v_mfma_f32_16x16x32_bf16 v[48:51], v[170:173], v[178:181], v[48:51]
	v_mfma_f32_16x16x32_bf16 v[36:39], v[162:165], v[190:193], v[36:39]
	v_mfma_f32_16x16x32_bf16 v[32:35], v[170:173], v[190:193], v[32:35]
	v_mfma_f32_16x16x32_bf16 v[20:23], v[162:165], v[198:201], v[20:23]
	v_mfma_f32_16x16x32_bf16 v[16:19], v[170:173], v[198:201], v[16:19]
	v_mfma_f32_16x16x32_bf16 v[4:7], v[162:165], v[206:209], v[4:7]
	v_mfma_f32_16x16x32_bf16 v[0:3], v[170:173], v[206:209], v[0:3]
	v_mfma_f32_16x16x32_bf16 v[52:55], v[166:169], v[186:189], v[52:55]
	v_mfma_f32_16x16x32_bf16 v[48:51], v[174:177], v[186:189], v[48:51]
	v_mfma_f32_16x16x32_bf16 v[36:39], v[166:169], v[194:197], v[36:39]
	v_mfma_f32_16x16x32_bf16 v[32:35], v[174:177], v[194:197], v[32:35]
	v_mfma_f32_16x16x32_bf16 v[20:23], v[166:169], v[202:205], v[20:23]
	v_mfma_f32_16x16x32_bf16 v[16:19], v[174:177], v[202:205], v[16:19]
	v_mfma_f32_16x16x32_bf16 v[4:7], v[166:169], v[210:213], v[4:7]
	v_mfma_f32_16x16x32_bf16 v[0:3], v[174:177], v[210:213], v[0:3]
	s_setprio 0
	s_barrier
	s_add_i32 s52, s52, 2
	s_add_u32 s26, s26, 0x100
	s_addc_u32 s27, s27, 0
	s_add_u32 s15, s15, 0x100
	s_addc_u32 s51, s51, 0
	s_cmp_gt_u32 s52, 61
	s_cbranch_scc0 .LBB0_960
	s_and_b64 vcc, exec, s[12:13]
	s_cbranch_vccz .LBB0_963
	s_barrier

.LBB0_1052:
	ds_read_b128 v[146:149], v142
	ds_read_b128 v[150:153], v142 offset:1024
	ds_read_b128 v[154:157], v142 offset:2048
	ds_read_b128 v[158:161], v142 offset:3072
	ds_read_b128 v[162:165], v143
	ds_read_b128 v[166:169], v143 offset:1024
	ds_read_b128 v[170:173], v143 offset:2048
	ds_read_b128 v[174:177], v143 offset:3072
	s_add_i32 s66, s40, 2
	s_add_u32 s67, s38, 0x80
	s_addc_u32 s41, s39, 0
	s_cmp_eq_u32 s57, s40
	s_cselect_b32 s40, s34, s67
	s_cselect_b32 s41, s35, s41
	s_cselect_b32 s69, s37, s65
	s_cselect_b32 s68, s36, s25
	v_lshl_add_u64 v[182:183], s[38:39], 0, v[136:137]
	s_add_i32 m0, s46, 0xc000
	ds_read_b128 v[178:181], v144
	ds_read_b128 v[186:189], v144 offset:1024
	ds_read_b128 v[190:193], v144 offset:2048
	ds_read_b128 v[194:197], v144 offset:3072
	ds_read_b128 v[198:201], v144 offset:4096
	ds_read_b128 v[202:205], v144 offset:5120
	ds_read_b128 v[206:209], v144 offset:6144
	ds_read_b128 v[210:213], v144 offset:7168
	global_load_lds_dwordx4 v[182:183], off
	v_lshl_add_u64 v[182:183], s[38:39], 0, v[138:139]
	s_add_i32 m0, s46, 0xe000
	s_nop 0
	global_load_lds_dwordx4 v[182:183], off
	s_waitcnt vmcnt(8)
	s_waitcnt lgkmcnt(0)
	s_barrier
	s_setprio 1
	s_waitcnt lgkmcnt(0)
	v_mfma_f32_16x16x32_bf16 v[124:127], v[146:149], v[178:181], v[124:127]
	v_mfma_f32_16x16x32_bf16 v[120:123], v[154:157], v[178:181], v[120:123]
	v_mfma_f32_16x16x32_bf16 v[108:111], v[146:149], v[190:193], v[108:111]
	v_mfma_f32_16x16x32_bf16 v[104:107], v[154:157], v[190:193], v[104:107]
	v_mfma_f32_16x16x32_bf16 v[92:95], v[146:149], v[198:201], v[92:95]
	v_mfma_f32_16x16x32_bf16 v[88:91], v[154:157], v[198:201], v[88:91]
	v_mfma_f32_16x16x32_bf16 v[76:79], v[146:149], v[206:209], v[76:79]
	v_mfma_f32_16x16x32_bf16 v[72:75], v[154:157], v[206:209], v[72:75]
	v_mfma_f32_16x16x32_bf16 v[124:127], v[150:153], v[186:189], v[124:127]
	v_mfma_f32_16x16x32_bf16 v[120:123], v[158:161], v[186:189], v[120:123]
	v_mfma_f32_16x16x32_bf16 v[108:111], v[150:153], v[194:197], v[108:111]
	v_mfma_f32_16x16x32_bf16 v[104:107], v[158:161], v[194:197], v[104:107]
	v_mfma_f32_16x16x32_bf16 v[92:95], v[150:153], v[202:205], v[92:95]
	v_mfma_f32_16x16x32_bf16 v[88:91], v[158:161], v[202:205], v[88:91]
	v_mfma_f32_16x16x32_bf16 v[76:79], v[150:153], v[210:213], v[76:79]
	v_mfma_f32_16x16x32_bf16 v[72:75], v[158:161], v[210:213], v[72:75]
	v_mfma_f32_16x16x32_bf16 v[116:119], v[162:165], v[178:181], v[116:119]
	v_mfma_f32_16x16x32_bf16 v[112:115], v[170:173], v[178:181], v[112:115]
	v_mfma_f32_16x16x32_bf16 v[100:103], v[162:165], v[190:193], v[100:103]
	v_mfma_f32_16x16x32_bf16 v[96:99], v[170:173], v[190:193], v[96:99]
	v_mfma_f32_16x16x32_bf16 v[84:87], v[162:165], v[198:201], v[84:87]
	v_mfma_f32_16x16x32_bf16 v[80:83], v[170:173], v[198:201], v[80:83]
	v_mfma_f32_16x16x32_bf16 v[68:71], v[162:165], v[206:209], v[68:71]
	v_mfma_f32_16x16x32_bf16 v[64:67], v[170:173], v[206:209], v[64:67]
	v_mfma_f32_16x16x32_bf16 v[116:119], v[166:169], v[186:189], v[116:119]
	v_mfma_f32_16x16x32_bf16 v[112:115], v[174:177], v[186:189], v[112:115]
	v_mfma_f32_16x16x32_bf16 v[100:103], v[166:169], v[194:197], v[100:103]
	v_mfma_f32_16x16x32_bf16 v[96:99], v[174:177], v[194:197], v[96:99]
	v_mfma_f32_16x16x32_bf16 v[84:87], v[166:169], v[202:205], v[84:87]
	v_mfma_f32_16x16x32_bf16 v[80:83], v[174:177], v[202:205], v[80:83]
	v_mfma_f32_16x16x32_bf16 v[68:71], v[166:169], v[210:213], v[68:71]
	v_mfma_f32_16x16x32_bf16 v[64:67], v[174:177], v[210:213], v[64:67]
	s_setprio 0
	s_barrier
	s_add_i32 s67, s58, s45
	v_lshl_add_u64 v[182:183], s[68:69], 0, v[132:133]
	s_mov_b32 m0, s67
	ds_read_b128 v[178:181], v144 offset:16384
	ds_read_b128 v[186:189], v144 offset:17408
	ds_read_b128 v[190:193], v144 offset:18432
	ds_read_b128 v[194:197], v144 offset:19456
	ds_read_b128 v[198:201], v144 offset:20480
	ds_read_b128 v[202:205], v144 offset:21504
	ds_read_b128 v[206:209], v144 offset:22528
	ds_read_b128 v[210:213], v144 offset:23552
	global_load_lds_dwordx4 v[182:183], off
	s_add_i32 m0, s67, 0x2000
	v_lshl_add_u64 v[214:215], s[68:69], 0, v[128:129]
	s_add_u32 s68, s68, s6
	s_addc_u32 s69, s69, s7
	s_add_i32 s67, s59, s45
	global_load_lds_dwordx4 v[214:215], off
	v_lshl_add_u64 v[216:217], s[68:69], 0, v[132:133]
	s_mov_b32 m0, s67
	v_lshl_add_u64 v[218:219], s[68:69], 0, v[128:129]
	global_load_lds_dwordx4 v[216:217], off
	s_add_i32 m0, s67, 0x2000
	v_lshl_add_u64 v[220:221], s[40:41], 0, v[134:135]
	global_load_lds_dwordx4 v[218:219], off
	s_mov_b32 m0, s46
	v_lshl_add_u64 v[222:223], s[40:41], 0, v[130:131]
	global_load_lds_dwordx4 v[220:221], off
	s_mov_b32 m0, s47
	s_nop 0
	global_load_lds_dwordx4 v[222:223], off
	s_waitcnt vmcnt(8)
	s_waitcnt lgkmcnt(0)
	s_barrier
	s_setprio 1
	s_waitcnt lgkmcnt(0)
	v_mfma_f32_16x16x32_bf16 v[60:63], v[146:149], v[178:181], v[60:63]
	v_mfma_f32_16x16x32_bf16 v[56:59], v[154:157], v[178:181], v[56:59]
	v_mfma_f32_16x16x32_bf16 v[44:47], v[146:149], v[190:193], v[44:47]
	v_mfma_f32_16x16x32_bf16 v[40:43], v[154:157], v[190:193], v[40:43]
	v_mfma_f32_16x16x32_bf16 v[28:31], v[146:149], v[198:201], v[28:31]
	v_mfma_f32_16x16x32_bf16 v[24:27], v[154:157], v[198:201], v[24:27]
	v_mfma_f32_16x16x32_bf16 v[12:15], v[146:149], v[206:209], v[12:15]
	v_mfma_f32_16x16x32_bf16 v[8:11], v[154:157], v[206:209], v[8:11]
	v_mfma_f32_16x16x32_bf16 v[60:63], v[150:153], v[186:189], v[60:63]
	v_mfma_f32_16x16x32_bf16 v[56:59], v[158:161], v[186:189], v[56:59]
	v_mfma_f32_16x16x32_bf16 v[44:47], v[150:153], v[194:197], v[44:47]
	v_mfma_f32_16x16x32_bf16 v[40:43], v[158:161], v[194:197], v[40:43]
	v_mfma_f32_16x16x32_bf16 v[28:31], v[150:153], v[202:205], v[28:31]
	v_mfma_f32_16x16x32_bf16 v[24:27], v[158:161], v[202:205], v[24:27]
	v_mfma_f32_16x16x32_bf16 v[12:15], v[150:153], v[210:213], v[12:15]
	v_mfma_f32_16x16x32_bf16 v[8:11], v[158:161], v[210:213], v[8:11]
	v_mfma_f32_16x16x32_bf16 v[52:55], v[162:165], v[178:181], v[52:55]
	v_mfma_f32_16x16x32_bf16 v[48:51], v[170:173], v[178:181], v[48:51]
	v_mfma_f32_16x16x32_bf16 v[36:39], v[162:165], v[190:193], v[36:39]
	v_mfma_f32_16x16x32_bf16 v[32:35], v[170:173], v[190:193], v[32:35]
	v_mfma_f32_16x16x32_bf16 v[20:23], v[162:165], v[198:201], v[20:23]
	v_mfma_f32_16x16x32_bf16 v[16:19], v[170:173], v[198:201], v[16:19]
	v_mfma_f32_16x16x32_bf16 v[4:7], v[162:165], v[206:209], v[4:7]
	v_mfma_f32_16x16x32_bf16 v[0:3], v[170:173], v[206:209], v[0:3]
	v_mfma_f32_16x16x32_bf16 v[52:55], v[166:169], v[186:189], v[52:55]
	v_mfma_f32_16x16x32_bf16 v[48:51], v[174:177], v[186:189], v[48:51]
	v_mfma_f32_16x16x32_bf16 v[36:39], v[166:169], v[194:197], v[36:39]
	v_mfma_f32_16x16x32_bf16 v[32:35], v[174:177], v[194:197], v[32:35]
	v_mfma_f32_16x16x32_bf16 v[20:23], v[166:169], v[202:205], v[20:23]
	v_mfma_f32_16x16x32_bf16 v[16:19], v[174:177], v[202:205], v[16:19]
	v_mfma_f32_16x16x32_bf16 v[4:7], v[166:169], v[210:213], v[4:7]
	v_mfma_f32_16x16x32_bf16 v[0:3], v[174:177], v[210:213], v[0:3]
	s_setprio 0
	s_barrier
	s_add_i32 s67, 0, 0x18000
	v_add_u32_e32 v145, s67, v141
	s_add_i32 s68, 0, 0x1c000
	ds_read_b128 v[146:149], v145
	ds_read_b128 v[150:153], v145 offset:1024
	ds_read_b128 v[154:157], v145 offset:2048
	ds_read_b128 v[158:161], v145 offset:3072
	v_add_u32_e32 v145, s68, v141
	ds_read_b128 v[162:165], v145
	ds_read_b128 v[166:169], v145 offset:1024
	ds_read_b128 v[170:173], v145 offset:2048
	ds_read_b128 v[174:177], v145 offset:3072
	s_add_u32 s40, s40, s6
	s_addc_u32 s41, s41, s7
	s_mov_b32 m0, s48
	v_lshl_add_u64 v[224:225], s[40:41], 0, v[134:135]
	ds_read_b128 v[178:181], v144 offset:32768
	ds_read_b128 v[186:189], v144 offset:33792
	ds_read_b128 v[190:193], v144 offset:34816
	ds_read_b128 v[194:197], v144 offset:35840
	ds_read_b128 v[198:201], v144 offset:36864
	ds_read_b128 v[202:205], v144 offset:37888
	ds_read_b128 v[206:209], v144 offset:38912
	ds_read_b128 v[210:213], v144 offset:39936
	global_load_lds_dwordx4 v[224:225], off
	v_lshl_add_u64 v[224:225], s[40:41], 0, v[130:131]
	s_mov_b32 m0, s49
	s_nop 0
	global_load_lds_dwordx4 v[224:225], off
	s_waitcnt vmcnt(8)
	s_waitcnt lgkmcnt(0)
	s_barrier
	s_setprio 1
	s_waitcnt lgkmcnt(0)
	v_mfma_f32_16x16x32_bf16 v[124:127], v[146:149], v[178:181], v[124:127]
	v_mfma_f32_16x16x32_bf16 v[120:123], v[154:157], v[178:181], v[120:123]
	v_mfma_f32_16x16x32_bf16 v[108:111], v[146:149], v[190:193], v[108:111]
	v_mfma_f32_16x16x32_bf16 v[104:107], v[154:157], v[190:193], v[104:107]
	v_mfma_f32_16x16x32_bf16 v[92:95], v[146:149], v[198:201], v[92:95]
	v_mfma_f32_16x16x32_bf16 v[88:91], v[154:157], v[198:201], v[88:91]
	v_mfma_f32_16x16x32_bf16 v[76:79], v[146:149], v[206:209], v[76:79]
	v_mfma_f32_16x16x32_bf16 v[72:75], v[154:157], v[206:209], v[72:75]
	v_mfma_f32_16x16x32_bf16 v[124:127], v[150:153], v[186:189], v[124:127]
	v_mfma_f32_16x16x32_bf16 v[120:123], v[158:161], v[186:189], v[120:123]
	v_mfma_f32_16x16x32_bf16 v[108:111], v[150:153], v[194:197], v[108:111]
	v_mfma_f32_16x16x32_bf16 v[104:107], v[158:161], v[194:197], v[104:107]
	v_mfma_f32_16x16x32_bf16 v[92:95], v[150:153], v[202:205], v[92:95]
	v_mfma_f32_16x16x32_bf16 v[88:91], v[158:161], v[202:205], v[88:91]
	v_mfma_f32_16x16x32_bf16 v[76:79], v[150:153], v[210:213], v[76:79]
	v_mfma_f32_16x16x32_bf16 v[72:75], v[158:161], v[210:213], v[72:75]
	v_mfma_f32_16x16x32_bf16 v[116:119], v[162:165], v[178:181], v[116:119]
	v_mfma_f32_16x16x32_bf16 v[112:115], v[170:173], v[178:181], v[112:115]
	v_mfma_f32_16x16x32_bf16 v[100:103], v[162:165], v[190:193], v[100:103]
	v_mfma_f32_16x16x32_bf16 v[96:99], v[170:173], v[190:193], v[96:99]
	v_mfma_f32_16x16x32_bf16 v[84:87], v[162:165], v[198:201], v[84:87]
	v_mfma_f32_16x16x32_bf16 v[80:83], v[170:173], v[198:201], v[80:83]
	v_mfma_f32_16x16x32_bf16 v[68:71], v[162:165], v[206:209], v[68:71]
	v_mfma_f32_16x16x32_bf16 v[64:67], v[170:173], v[206:209], v[64:67]
	v_mfma_f32_16x16x32_bf16 v[116:119], v[166:169], v[186:189], v[116:119]
	v_mfma_f32_16x16x32_bf16 v[112:115], v[174:177], v[186:189], v[112:115]
	v_mfma_f32_16x16x32_bf16 v[100:103], v[166:169], v[194:197], v[100:103]
	v_mfma_f32_16x16x32_bf16 v[96:99], v[174:177], v[194:197], v[96:99]
	v_mfma_f32_16x16x32_bf16 v[84:87], v[166:169], v[202:205], v[84:87]
	v_mfma_f32_16x16x32_bf16 v[80:83], v[174:177], v[202:205], v[80:83]
	v_mfma_f32_16x16x32_bf16 v[68:71], v[166:169], v[210:213], v[68:71]
	v_mfma_f32_16x16x32_bf16 v[64:67], v[174:177], v[210:213], v[64:67]
	s_setprio 0
	s_barrier
	s_add_i32 s40, s67, s45
	v_lshl_add_u64 v[182:183], v[182:183], 0, s[10:11]
	s_mov_b32 m0, s40
	ds_read_b128 v[178:181], v144 offset:49152
	ds_read_b128 v[186:189], v144 offset:50176
	ds_read_b128 v[190:193], v144 offset:51200
	ds_read_b128 v[194:197], v144 offset:52224
	ds_read_b128 v[198:201], v144 offset:53248
	ds_read_b128 v[202:205], v144 offset:54272
	ds_read_b128 v[206:209], v144 offset:55296
	ds_read_b128 v[210:213], v144 offset:56320
	global_load_lds_dwordx4 v[182:183], off
	v_lshl_add_u64 v[182:183], v[214:215], 0, s[10:11]
	s_add_i32 m0, s40, 0x2000
	s_add_i32 s40, s68, s45
	global_load_lds_dwordx4 v[182:183], off
	v_lshl_add_u64 v[182:183], v[216:217], 0, s[10:11]
	s_mov_b32 m0, s40
	s_nop 0
	global_load_lds_dwordx4 v[182:183], off
	v_lshl_add_u64 v[182:183], v[218:219], 0, s[10:11]
	s_add_i32 m0, s40, 0x2000
	s_nop 0
	global_load_lds_dwordx4 v[182:183], off
	v_lshl_add_u64 v[182:183], v[220:221], 0, s[10:11]
	s_mov_b32 m0, s52
	s_nop 0
	global_load_lds_dwordx4 v[182:183], off
	v_lshl_add_u64 v[182:183], v[222:223], 0, s[10:11]
	s_mov_b32 m0, s53
	s_nop 0
	global_load_lds_dwordx4 v[182:183], off
	s_waitcnt vmcnt(8)
	s_waitcnt lgkmcnt(0)
	s_barrier
	s_setprio 1
	s_waitcnt lgkmcnt(0)
	v_mfma_f32_16x16x32_bf16 v[60:63], v[146:149], v[178:181], v[60:63]
	v_mfma_f32_16x16x32_bf16 v[56:59], v[154:157], v[178:181], v[56:59]
	v_mfma_f32_16x16x32_bf16 v[44:47], v[146:149], v[190:193], v[44:47]
	v_mfma_f32_16x16x32_bf16 v[40:43], v[154:157], v[190:193], v[40:43]
	v_mfma_f32_16x16x32_bf16 v[28:31], v[146:149], v[198:201], v[28:31]
	v_mfma_f32_16x16x32_bf16 v[24:27], v[154:157], v[198:201], v[24:27]
	v_mfma_f32_16x16x32_bf16 v[12:15], v[146:149], v[206:209], v[12:15]
	v_mfma_f32_16x16x32_bf16 v[8:11], v[154:157], v[206:209], v[8:11]
	v_mfma_f32_16x16x32_bf16 v[60:63], v[150:153], v[186:189], v[60:63]
	v_mfma_f32_16x16x32_bf16 v[56:59], v[158:161], v[186:189], v[56:59]
	v_mfma_f32_16x16x32_bf16 v[44:47], v[150:153], v[194:197], v[44:47]
	v_mfma_f32_16x16x32_bf16 v[40:43], v[158:161], v[194:197], v[40:43]
	v_mfma_f32_16x16x32_bf16 v[28:31], v[150:153], v[202:205], v[28:31]
	v_mfma_f32_16x16x32_bf16 v[24:27], v[158:161], v[202:205], v[24:27]
	v_mfma_f32_16x16x32_bf16 v[12:15], v[150:153], v[210:213], v[12:15]
	v_mfma_f32_16x16x32_bf16 v[8:11], v[158:161], v[210:213], v[8:11]
	v_mfma_f32_16x16x32_bf16 v[52:55], v[162:165], v[178:181], v[52:55]
	v_mfma_f32_16x16x32_bf16 v[48:51], v[170:173], v[178:181], v[48:51]
	v_mfma_f32_16x16x32_bf16 v[36:39], v[162:165], v[190:193], v[36:39]
	v_mfma_f32_16x16x32_bf16 v[32:35], v[170:173], v[190:193], v[32:35]
	v_mfma_f32_16x16x32_bf16 v[20:23], v[162:165], v[198:201], v[20:23]
	v_mfma_f32_16x16x32_bf16 v[16:19], v[170:173], v[198:201], v[16:19]
	v_mfma_f32_16x16x32_bf16 v[4:7], v[162:165], v[206:209], v[4:7]
	v_mfma_f32_16x16x32_bf16 v[0:3], v[170:173], v[206:209], v[0:3]
	v_mfma_f32_16x16x32_bf16 v[52:55], v[166:169], v[186:189], v[52:55]
	v_mfma_f32_16x16x32_bf16 v[48:51], v[174:177], v[186:189], v[48:51]
	v_mfma_f32_16x16x32_bf16 v[36:39], v[166:169], v[194:197], v[36:39]
	v_mfma_f32_16x16x32_bf16 v[32:35], v[174:177], v[194:197], v[32:35]
	v_mfma_f32_16x16x32_bf16 v[20:23], v[166:169], v[202:205], v[20:23]
	v_mfma_f32_16x16x32_bf16 v[16:19], v[174:177], v[202:205], v[16:19]
	v_mfma_f32_16x16x32_bf16 v[4:7], v[166:169], v[210:213], v[4:7]
	v_mfma_f32_16x16x32_bf16 v[0:3], v[174:177], v[210:213], v[0:3]
	s_setprio 0
	s_barrier
	s_add_u32 s38, s38, 0x100
	s_addc_u32 s39, s39, 0
	s_add_u32 s25, s25, 0x100
	s_addc_u32 s65, s65, 0
	s_cmp_ge_i32 s66, s54
	s_mov_b32 s40, s66
	s_cbranch_scc0 .LBB0_1052

.LBB0_1074:
	ds_read_b128 v[140:143], v150
	ds_read_b128 v[144:147], v150 offset:1024
	ds_read_b128 v[156:159], v150 offset:2048
	ds_read_b128 v[160:163], v150 offset:3072
	ds_read_b128 v[164:167], v151
	ds_read_b128 v[168:171], v151 offset:1024
	ds_read_b128 v[172:175], v151 offset:2048
	ds_read_b128 v[176:179], v151 offset:3072
	s_add_u32 s30, s28, 0xfffc0080
	s_addc_u32 s31, s29, -1
	s_cmp_eq_u32 s23, 12
	s_cselect_b32 s35, s25, s31
	s_cselect_b32 s34, s24, s30
	s_cselect_b32 s31, s27, s15
	s_cselect_b32 s30, s26, s0
	v_lshl_add_u64 v[214:215], s[28:29], 0, v[136:137]
	s_add_i32 m0, s39, 0xc000
	ds_read_b128 v[180:183], v152
	ds_read_b128 v[186:189], v152 offset:1024
	ds_read_b128 v[190:193], v152 offset:2048
	ds_read_b128 v[194:197], v152 offset:3072
	ds_read_b128 v[198:201], v152 offset:4096
	ds_read_b128 v[202:205], v152 offset:5120
	ds_read_b128 v[206:209], v152 offset:6144
	ds_read_b128 v[210:213], v152 offset:7168
	global_load_lds_dwordx4 v[214:215], off
	v_lshl_add_u64 v[214:215], s[28:29], 0, v[138:139]
	s_add_i32 m0, s39, 0xe000
	s_nop 0
	global_load_lds_dwordx4 v[214:215], off
	s_waitcnt vmcnt(8)
	s_waitcnt lgkmcnt(0)
	s_barrier
	s_setprio 1
	s_waitcnt lgkmcnt(0)
	v_mfma_f32_16x16x32_bf16 v[124:127], v[140:143], v[180:183], v[124:127]
	v_mfma_f32_16x16x32_bf16 v[120:123], v[156:159], v[180:183], v[120:123]
	v_mfma_f32_16x16x32_bf16 v[108:111], v[140:143], v[190:193], v[108:111]
	v_mfma_f32_16x16x32_bf16 v[104:107], v[156:159], v[190:193], v[104:107]
	v_mfma_f32_16x16x32_bf16 v[92:95], v[140:143], v[198:201], v[92:95]
	v_mfma_f32_16x16x32_bf16 v[88:91], v[156:159], v[198:201], v[88:91]
	v_mfma_f32_16x16x32_bf16 v[76:79], v[140:143], v[206:209], v[76:79]
	v_mfma_f32_16x16x32_bf16 v[72:75], v[156:159], v[206:209], v[72:75]
	v_mfma_f32_16x16x32_bf16 v[124:127], v[144:147], v[186:189], v[124:127]
	v_mfma_f32_16x16x32_bf16 v[120:123], v[160:163], v[186:189], v[120:123]
	v_mfma_f32_16x16x32_bf16 v[108:111], v[144:147], v[194:197], v[108:111]
	v_mfma_f32_16x16x32_bf16 v[104:107], v[160:163], v[194:197], v[104:107]
	v_mfma_f32_16x16x32_bf16 v[92:95], v[144:147], v[202:205], v[92:95]
	v_mfma_f32_16x16x32_bf16 v[88:91], v[160:163], v[202:205], v[88:91]
	v_mfma_f32_16x16x32_bf16 v[76:79], v[144:147], v[210:213], v[76:79]
	v_mfma_f32_16x16x32_bf16 v[72:75], v[160:163], v[210:213], v[72:75]
	v_mfma_f32_16x16x32_bf16 v[116:119], v[164:167], v[180:183], v[116:119]
	v_mfma_f32_16x16x32_bf16 v[112:115], v[172:175], v[180:183], v[112:115]
	v_mfma_f32_16x16x32_bf16 v[100:103], v[164:167], v[190:193], v[100:103]
	v_mfma_f32_16x16x32_bf16 v[96:99], v[172:175], v[190:193], v[96:99]
	v_mfma_f32_16x16x32_bf16 v[84:87], v[164:167], v[198:201], v[84:87]
	v_mfma_f32_16x16x32_bf16 v[80:83], v[172:175], v[198:201], v[80:83]
	v_mfma_f32_16x16x32_bf16 v[68:71], v[164:167], v[206:209], v[68:71]
	v_mfma_f32_16x16x32_bf16 v[64:67], v[172:175], v[206:209], v[64:67]
	v_mfma_f32_16x16x32_bf16 v[116:119], v[168:171], v[186:189], v[116:119]
	v_mfma_f32_16x16x32_bf16 v[112:115], v[176:179], v[186:189], v[112:115]
	v_mfma_f32_16x16x32_bf16 v[100:103], v[168:171], v[194:197], v[100:103]
	v_mfma_f32_16x16x32_bf16 v[96:99], v[176:179], v[194:197], v[96:99]
	v_mfma_f32_16x16x32_bf16 v[84:87], v[168:171], v[202:205], v[84:87]
	v_mfma_f32_16x16x32_bf16 v[80:83], v[176:179], v[202:205], v[80:83]
	v_mfma_f32_16x16x32_bf16 v[68:71], v[168:171], v[210:213], v[68:71]
	v_mfma_f32_16x16x32_bf16 v[64:67], v[176:179], v[210:213], v[64:67]
	s_setprio 0
	s_barrier
	s_add_i32 s52, s48, s38
	v_lshl_add_u64 v[214:215], s[30:31], 0, v[130:131]
	s_mov_b32 m0, s52
	ds_read_b128 v[180:183], v152 offset:16384
	ds_read_b128 v[186:189], v152 offset:17408
	ds_read_b128 v[190:193], v152 offset:18432
	ds_read_b128 v[194:197], v152 offset:19456
	ds_read_b128 v[198:201], v152 offset:20480
	ds_read_b128 v[202:205], v152 offset:21504
	ds_read_b128 v[206:209], v152 offset:22528
	ds_read_b128 v[210:213], v152 offset:23552
	global_load_lds_dwordx4 v[214:215], off
	s_add_i32 m0, s52, 0x2000
	s_add_u32 s52, s30, 0x40000
	v_lshl_add_u64 v[216:217], s[30:31], 0, v[134:135]
	s_addc_u32 s53, s31, 0
	s_add_i32 s54, s49, s38
	global_load_lds_dwordx4 v[216:217], off
	v_lshl_add_u64 v[218:219], s[52:53], 0, v[130:131]
	s_mov_b32 m0, s54
	v_lshl_add_u64 v[220:221], s[34:35], 0, v[132:133]
	global_load_lds_dwordx4 v[218:219], off
	v_lshl_add_u64 v[218:219], s[52:53], 0, v[134:135]
	s_add_i32 m0, s54, 0x2000
	s_nop 0
	global_load_lds_dwordx4 v[218:219], off
	v_lshl_add_u64 v[218:219], s[34:35], 0, v[128:129]
	s_mov_b32 m0, s39
	s_nop 0
	global_load_lds_dwordx4 v[218:219], off
	s_mov_b32 m0, s40
	s_nop 0
	global_load_lds_dwordx4 v[220:221], off
	s_waitcnt vmcnt(8)
	s_waitcnt lgkmcnt(0)
	s_barrier
	s_setprio 1
	s_waitcnt lgkmcnt(0)
	v_mfma_f32_16x16x32_bf16 v[60:63], v[140:143], v[180:183], v[60:63]
	v_mfma_f32_16x16x32_bf16 v[56:59], v[156:159], v[180:183], v[56:59]
	v_mfma_f32_16x16x32_bf16 v[44:47], v[140:143], v[190:193], v[44:47]
	v_mfma_f32_16x16x32_bf16 v[40:43], v[156:159], v[190:193], v[40:43]
	v_mfma_f32_16x16x32_bf16 v[28:31], v[140:143], v[198:201], v[28:31]
	v_mfma_f32_16x16x32_bf16 v[24:27], v[156:159], v[198:201], v[24:27]
	v_mfma_f32_16x16x32_bf16 v[12:15], v[140:143], v[206:209], v[12:15]
	v_mfma_f32_16x16x32_bf16 v[8:11], v[156:159], v[206:209], v[8:11]
	v_mfma_f32_16x16x32_bf16 v[60:63], v[144:147], v[186:189], v[60:63]
	v_mfma_f32_16x16x32_bf16 v[56:59], v[160:163], v[186:189], v[56:59]
	v_mfma_f32_16x16x32_bf16 v[44:47], v[144:147], v[194:197], v[44:47]
	v_mfma_f32_16x16x32_bf16 v[40:43], v[160:163], v[194:197], v[40:43]
	v_mfma_f32_16x16x32_bf16 v[28:31], v[144:147], v[202:205], v[28:31]
	v_mfma_f32_16x16x32_bf16 v[24:27], v[160:163], v[202:205], v[24:27]
	v_mfma_f32_16x16x32_bf16 v[12:15], v[144:147], v[210:213], v[12:15]
	v_mfma_f32_16x16x32_bf16 v[8:11], v[160:163], v[210:213], v[8:11]
	v_mfma_f32_16x16x32_bf16 v[52:55], v[164:167], v[180:183], v[52:55]
	v_mfma_f32_16x16x32_bf16 v[48:51], v[172:175], v[180:183], v[48:51]
	v_mfma_f32_16x16x32_bf16 v[36:39], v[164:167], v[190:193], v[36:39]
	v_mfma_f32_16x16x32_bf16 v[32:35], v[172:175], v[190:193], v[32:35]
	v_mfma_f32_16x16x32_bf16 v[20:23], v[164:167], v[198:201], v[20:23]
	v_mfma_f32_16x16x32_bf16 v[16:19], v[172:175], v[198:201], v[16:19]
	v_mfma_f32_16x16x32_bf16 v[4:7], v[164:167], v[206:209], v[4:7]
	v_mfma_f32_16x16x32_bf16 v[0:3], v[172:175], v[206:209], v[0:3]
	v_mfma_f32_16x16x32_bf16 v[52:55], v[168:171], v[186:189], v[52:55]
	v_mfma_f32_16x16x32_bf16 v[48:51], v[176:179], v[186:189], v[48:51]
	v_mfma_f32_16x16x32_bf16 v[36:39], v[168:171], v[194:197], v[36:39]
	v_mfma_f32_16x16x32_bf16 v[32:35], v[176:179], v[194:197], v[32:35]
	v_mfma_f32_16x16x32_bf16 v[20:23], v[168:171], v[202:205], v[20:23]
	v_mfma_f32_16x16x32_bf16 v[16:19], v[176:179], v[202:205], v[16:19]
	v_mfma_f32_16x16x32_bf16 v[4:7], v[168:171], v[210:213], v[4:7]
	v_mfma_f32_16x16x32_bf16 v[0:3], v[176:179], v[210:213], v[0:3]
	s_setprio 0
	s_barrier
	s_add_i32 s52, 0, 0x18000
	v_add_u32_e32 v155, s52, v149
	s_add_i32 s53, 0, 0x1c000
	ds_read_b128 v[140:143], v155
	ds_read_b128 v[144:147], v155 offset:1024
	ds_read_b128 v[156:159], v155 offset:2048
	ds_read_b128 v[160:163], v155 offset:3072
	v_add_u32_e32 v155, s53, v149
	ds_read_b128 v[164:167], v155
	ds_read_b128 v[168:171], v155 offset:1024
	ds_read_b128 v[172:175], v155 offset:2048
	ds_read_b128 v[176:179], v155 offset:3072
	s_add_u32 s34, s34, 0x40000
	s_addc_u32 s35, s35, 0
	s_mov_b32 m0, s41
	v_lshl_add_u64 v[222:223], s[34:35], 0, v[128:129]
	ds_read_b128 v[180:183], v152 offset:32768
	ds_read_b128 v[186:189], v152 offset:33792
	ds_read_b128 v[190:193], v152 offset:34816
	ds_read_b128 v[194:197], v152 offset:35840
	ds_read_b128 v[198:201], v152 offset:36864
	ds_read_b128 v[202:205], v152 offset:37888
	ds_read_b128 v[206:209], v152 offset:38912
	ds_read_b128 v[210:213], v152 offset:39936
	global_load_lds_dwordx4 v[222:223], off
	v_lshl_add_u64 v[222:223], s[34:35], 0, v[132:133]
	s_mov_b32 m0, s42
	s_nop 0
	global_load_lds_dwordx4 v[222:223], off
	s_waitcnt vmcnt(8)
	s_waitcnt lgkmcnt(0)
	s_barrier
	s_setprio 1
	s_waitcnt lgkmcnt(0)
	v_mfma_f32_16x16x32_bf16 v[124:127], v[140:143], v[180:183], v[124:127]
	v_mfma_f32_16x16x32_bf16 v[120:123], v[156:159], v[180:183], v[120:123]
	v_mfma_f32_16x16x32_bf16 v[108:111], v[140:143], v[190:193], v[108:111]
	v_mfma_f32_16x16x32_bf16 v[104:107], v[156:159], v[190:193], v[104:107]
	v_mfma_f32_16x16x32_bf16 v[92:95], v[140:143], v[198:201], v[92:95]
	v_mfma_f32_16x16x32_bf16 v[88:91], v[156:159], v[198:201], v[88:91]
	v_mfma_f32_16x16x32_bf16 v[76:79], v[140:143], v[206:209], v[76:79]
	v_mfma_f32_16x16x32_bf16 v[72:75], v[156:159], v[206:209], v[72:75]
	v_mfma_f32_16x16x32_bf16 v[124:127], v[144:147], v[186:189], v[124:127]
	v_mfma_f32_16x16x32_bf16 v[120:123], v[160:163], v[186:189], v[120:123]
	v_mfma_f32_16x16x32_bf16 v[108:111], v[144:147], v[194:197], v[108:111]
	v_mfma_f32_16x16x32_bf16 v[104:107], v[160:163], v[194:197], v[104:107]
	v_mfma_f32_16x16x32_bf16 v[92:95], v[144:147], v[202:205], v[92:95]
	v_mfma_f32_16x16x32_bf16 v[88:91], v[160:163], v[202:205], v[88:91]
	v_mfma_f32_16x16x32_bf16 v[76:79], v[144:147], v[210:213], v[76:79]
	v_mfma_f32_16x16x32_bf16 v[72:75], v[160:163], v[210:213], v[72:75]
	v_mfma_f32_16x16x32_bf16 v[116:119], v[164:167], v[180:183], v[116:119]
	v_mfma_f32_16x16x32_bf16 v[112:115], v[172:175], v[180:183], v[112:115]
	v_mfma_f32_16x16x32_bf16 v[100:103], v[164:167], v[190:193], v[100:103]
	v_mfma_f32_16x16x32_bf16 v[96:99], v[172:175], v[190:193], v[96:99]
	v_mfma_f32_16x16x32_bf16 v[84:87], v[164:167], v[198:201], v[84:87]
	v_mfma_f32_16x16x32_bf16 v[80:83], v[172:175], v[198:201], v[80:83]
	v_mfma_f32_16x16x32_bf16 v[68:71], v[164:167], v[206:209], v[68:71]
	v_mfma_f32_16x16x32_bf16 v[64:67], v[172:175], v[206:209], v[64:67]
	v_mfma_f32_16x16x32_bf16 v[116:119], v[168:171], v[186:189], v[116:119]
	v_mfma_f32_16x16x32_bf16 v[112:115], v[176:179], v[186:189], v[112:115]
	v_mfma_f32_16x16x32_bf16 v[100:103], v[168:171], v[194:197], v[100:103]
	v_mfma_f32_16x16x32_bf16 v[96:99], v[176:179], v[194:197], v[96:99]
	v_mfma_f32_16x16x32_bf16 v[84:87], v[168:171], v[202:205], v[84:87]
	v_mfma_f32_16x16x32_bf16 v[80:83], v[176:179], v[202:205], v[80:83]
	v_mfma_f32_16x16x32_bf16 v[68:71], v[168:171], v[210:213], v[68:71]
	v_mfma_f32_16x16x32_bf16 v[64:67], v[176:179], v[210:213], v[64:67]
	s_setprio 0
	s_barrier
	s_add_i32 s34, s52, s38
	v_lshl_add_u64 v[214:215], v[214:215], 0, s[10:11]
	s_mov_b32 m0, s34
	ds_read_b128 v[180:183], v152 offset:49152
	ds_read_b128 v[186:189], v152 offset:50176
	ds_read_b128 v[190:193], v152 offset:51200
	ds_read_b128 v[194:197], v152 offset:52224
	ds_read_b128 v[198:201], v152 offset:53248
	ds_read_b128 v[202:205], v152 offset:54272
	ds_read_b128 v[206:209], v152 offset:55296
	ds_read_b128 v[210:213], v152 offset:56320
	global_load_lds_dwordx4 v[214:215], off
	s_add_i32 m0, s34, 0x2000
	s_add_u32 s30, s30, 0x40080
	v_lshl_add_u64 v[214:215], v[216:217], 0, s[10:11]
	s_addc_u32 s31, s31, 0
	s_add_i32 s34, s53, s38
	global_load_lds_dwordx4 v[214:215], off
	v_lshl_add_u64 v[214:215], s[30:31], 0, v[130:131]
	s_mov_b32 m0, s34
	s_nop 0
	global_load_lds_dwordx4 v[214:215], off
	v_lshl_add_u64 v[214:215], s[30:31], 0, v[134:135]
	s_add_i32 m0, s34, 0x2000
	s_nop 0
	global_load_lds_dwordx4 v[214:215], off
	v_lshl_add_u64 v[214:215], v[218:219], 0, s[10:11]
	s_mov_b32 m0, s46
	s_nop 0
	global_load_lds_dwordx4 v[214:215], off
	v_lshl_add_u64 v[214:215], v[220:221], 0, s[10:11]
	s_mov_b32 m0, s47
	s_nop 0
	global_load_lds_dwordx4 v[214:215], off
	s_waitcnt vmcnt(8)
	s_waitcnt lgkmcnt(0)
	s_barrier
	s_setprio 1
	s_waitcnt lgkmcnt(0)
	v_mfma_f32_16x16x32_bf16 v[60:63], v[140:143], v[180:183], v[60:63]
	v_mfma_f32_16x16x32_bf16 v[56:59], v[156:159], v[180:183], v[56:59]
	v_mfma_f32_16x16x32_bf16 v[44:47], v[140:143], v[190:193], v[44:47]
	v_mfma_f32_16x16x32_bf16 v[40:43], v[156:159], v[190:193], v[40:43]
	v_mfma_f32_16x16x32_bf16 v[28:31], v[140:143], v[198:201], v[28:31]
	v_mfma_f32_16x16x32_bf16 v[24:27], v[156:159], v[198:201], v[24:27]
	v_mfma_f32_16x16x32_bf16 v[12:15], v[140:143], v[206:209], v[12:15]
	v_mfma_f32_16x16x32_bf16 v[8:11], v[156:159], v[206:209], v[8:11]
	v_mfma_f32_16x16x32_bf16 v[60:63], v[144:147], v[186:189], v[60:63]
	v_mfma_f32_16x16x32_bf16 v[56:59], v[160:163], v[186:189], v[56:59]
	v_mfma_f32_16x16x32_bf16 v[44:47], v[144:147], v[194:197], v[44:47]
	v_mfma_f32_16x16x32_bf16 v[40:43], v[160:163], v[194:197], v[40:43]
	v_mfma_f32_16x16x32_bf16 v[28:31], v[144:147], v[202:205], v[28:31]
	v_mfma_f32_16x16x32_bf16 v[24:27], v[160:163], v[202:205], v[24:27]
	v_mfma_f32_16x16x32_bf16 v[12:15], v[144:147], v[210:213], v[12:15]
	v_mfma_f32_16x16x32_bf16 v[8:11], v[160:163], v[210:213], v[8:11]
	v_mfma_f32_16x16x32_bf16 v[52:55], v[164:167], v[180:183], v[52:55]
	v_mfma_f32_16x16x32_bf16 v[48:51], v[172:175], v[180:183], v[48:51]
	v_mfma_f32_16x16x32_bf16 v[36:39], v[164:167], v[190:193], v[36:39]
	v_mfma_f32_16x16x32_bf16 v[32:35], v[172:175], v[190:193], v[32:35]
	v_mfma_f32_16x16x32_bf16 v[20:23], v[164:167], v[198:201], v[20:23]
	v_mfma_f32_16x16x32_bf16 v[16:19], v[172:175], v[198:201], v[16:19]
	v_mfma_f32_16x16x32_bf16 v[4:7], v[164:167], v[206:209], v[4:7]
	v_mfma_f32_16x16x32_bf16 v[0:3], v[172:175], v[206:209], v[0:3]
	v_mfma_f32_16x16x32_bf16 v[52:55], v[168:171], v[186:189], v[52:55]
	v_mfma_f32_16x16x32_bf16 v[48:51], v[176:179], v[186:189], v[48:51]
	v_mfma_f32_16x16x32_bf16 v[36:39], v[168:171], v[194:197], v[36:39]
	v_mfma_f32_16x16x32_bf16 v[32:35], v[176:179], v[194:197], v[32:35]
	v_mfma_f32_16x16x32_bf16 v[20:23], v[168:171], v[202:205], v[20:23]
	v_mfma_f32_16x16x32_bf16 v[16:19], v[176:179], v[202:205], v[16:19]
	v_mfma_f32_16x16x32_bf16 v[4:7], v[168:171], v[210:213], v[4:7]
	v_mfma_f32_16x16x32_bf16 v[0:3], v[176:179], v[210:213], v[0:3]
	s_setprio 0
	s_barrier
	s_add_i32 s23, s23, 2
	s_add_u32 s28, s28, 0x100
	s_addc_u32 s29, s29, 0
	s_add_u32 s0, s0, 0x100
	s_addc_u32 s15, s15, 0
	s_cmp_gt_u32 s23, 13
	s_cbranch_scc0 .LBB0_1074
	s_and_b64 vcc, exec, s[12:13]
	s_cbranch_vccz .LBB0_1077
	s_barrier
